# E4: batched the 32 y loads per half (one round trip instead of eight) and rewrote the 64x64 state-by-query product with packed f32 fma on natural register pairs (784 register moves removed); odd atten
# speedup vs baseline: 1.0303x; 1.0105x over previous
.LBB0_425:
	v_mov_b32_e32 v52, v228
	s_mul_i32 s3, s5, 0x1800
	v_ashrrev_i32_e32 v16, 31, v52
	v_lshrrev_b32_e32 v16, 28, v16
	v_add_u32_e32 v16, v52, v16
	v_ashrrev_i32_e32 v124, 4, v16
	v_and_b32_e32 v56, -16, v16
	v_add_u32_e32 v16, 0x100, v52
	v_ashrrev_i32_e32 v17, 31, v16
	s_mul_hi_u32 s16, s4, 0x1800
	v_lshrrev_b32_e32 v17, 28, v17
	v_add_u32_e32 v18, 0x300, v52
	s_add_i32 s16, s16, s3
	s_mul_i32 s3, s4, 0x1800
	v_add_u32_e32 v17, v16, v17
	v_ashrrev_i32_e32 v19, 31, v18
	s_add_u32 s3, s44, s3
	v_and_b32_e32 v58, -16, v17
	v_lshrrev_b32_e32 v19, 28, v19
	s_addc_u32 s17, s45, s16
	s_lshl_b64 s[12:13], s[12:13], 1
	v_sub_u32_e32 v59, v16, v58
	v_add_u32_e32 v16, 0x200, v52
	v_add_u32_e32 v19, v18, v19
	s_add_u32 s16, s3, s12
	v_ashrrev_i32_e32 v126, 4, v17
	v_ashrrev_i32_e32 v17, 31, v16
	v_and_b32_e32 v62, -16, v19
	s_addc_u32 s17, s17, s13
	v_lshrrev_b32_e32 v17, 28, v17
	v_ashrrev_i32_e32 v130, 4, v19
	v_sub_u32_e32 v63, v18, v62
	v_mov_b64_e32 v[0:1], s[16:17]
	v_lshlrev_b32_e32 v26, 3, v59
	v_add_u32_e32 v17, v16, v17
	v_lshlrev_b32_e32 v18, 3, v63
	v_mad_i64_i32 v[20:21], s[16:17], s10, v130, 0
	v_mad_i64_i32 v[32:33], s[16:17], s10, v126, 0
	v_ashrrev_i32_e32 v27, 31, v26
	v_and_b32_e32 v60, -16, v17
	v_ashrrev_i32_e32 v19, 31, v18
	v_lshlrev_b64 v[28:29], 1, v[20:21]
	v_lshlrev_b64 v[48:49], 1, v[32:33]
	v_sub_u32_e32 v57, v52, v56
	v_ashrrev_i32_e32 v128, 4, v17
	v_sub_u32_e32 v61, v16, v60
	v_lshl_add_u64 v[20:21], s[8:9], 0, v[28:29]
	v_lshlrev_b64 v[132:133], 1, v[18:19]
	v_lshl_add_u64 v[32:33], s[8:9], 0, v[48:49]
	v_lshlrev_b64 v[136:137], 1, v[26:27]
	v_ashrrev_i32_e32 v53, 6, v52
	v_and_b32_e32 v55, 15, v52
	v_lshlrev_b32_e32 v24, 3, v57
	v_lshlrev_b32_e32 v16, 3, v61
	v_lshl_add_u64 v[18:19], v[20:21], 0, v[132:133]
	v_mad_i64_i32 v[20:21], s[16:17], s10, v128, 0
	v_lshl_add_u64 v[26:27], v[32:33], 0, v[136:137]
	v_mad_i64_i32 v[32:33], s[16:17], s10, v124, 0
	v_bfe_u32 v54, v52, 4, 2
	v_lshl_or_b32 v122, v53, 4, v55
	v_ashrrev_i32_e32 v25, 31, v24
	v_ashrrev_i32_e32 v17, 31, v16
	v_lshlrev_b64 v[30:31], 1, v[20:21]
	v_lshlrev_b64 v[50:51], 1, v[32:33]
	v_mad_i64_i32 v[0:1], s[16:17], v122, s28, v[0:1]
	v_lshlrev_b32_e32 v196, 4, v54
	v_lshl_add_u64 v[20:21], s[8:9], 0, v[30:31]
	v_lshlrev_b64 v[134:135], 1, v[16:17]
	v_lshl_add_u64 v[32:33], s[8:9], 0, v[50:51]
	v_lshlrev_b64 v[138:139], 1, v[24:25]
	v_lshl_add_u64 v[12:13], v[0:1], 0, v[196:197]
	v_lshl_add_u64 v[16:17], v[20:21], 0, v[134:135]
	v_lshl_add_u64 v[24:25], v[32:33], 0, v[138:139]
	global_load_dwordx4 v[0:3], v[12:13], off
	global_load_dwordx4 v[4:7], v[12:13], off offset:64
	global_load_dwordx4 v[8:11], v[12:13], off offset:128
	s_nop 0
	global_load_dwordx4 v[12:15], v[12:13], off offset:192
	s_nop 0
	global_load_dwordx4 v[20:23], v[18:19], off
	s_nop 0
	global_load_dwordx4 v[16:19], v[16:17], off
	s_nop 0
	global_load_dwordx4 v[36:39], v[26:27], off
	global_load_dwordx4 v[32:35], v[24:25], off
	v_lshl_add_u64 v[24:25], s[6:7], 0, v[28:29]
	v_lshl_add_u64 v[26:27], s[6:7], 0, v[30:31]
	v_lshl_add_u64 v[24:25], v[24:25], 0, v[132:133]
	v_lshl_add_u64 v[26:27], v[26:27], 0, v[134:135]
	global_load_dwordx4 v[44:47], v[24:25], off
	global_load_dwordx4 v[40:43], v[26:27], off
	v_lshl_add_u64 v[24:25], s[6:7], 0, v[48:49]
	v_lshl_add_u64 v[26:27], s[6:7], 0, v[50:51]
	v_lshl_add_u64 v[24:25], v[24:25], 0, v[136:137]
	v_lshl_add_u64 v[26:27], v[26:27], 0, v[138:139]
	global_load_dwordx4 v[28:31], v[24:25], off
	s_nop 0
	global_load_dwordx4 v[24:27], v[26:27], off
	s_add_u32 s3, s44, s14
	s_addc_u32 s14, s45, s15
	s_add_u32 s3, s3, s12
	s_addc_u32 s17, s14, s13
	v_lshlrev_b32_e32 v120, 3, v54
	v_bfe_u32 v50, v52, 2, 2
	s_movk_i32 s19, 0x120
	s_add_u32 s14, s3, 0x800
	v_lshl_or_b32 v48, v53, 5, v55
	v_or_b32_e32 v50, v120, v50
	v_lshlrev_b32_e32 v51, 3, v52
	v_mul_lo_u32 v129, v124, s19
	v_mul_lo_u32 v141, v126, s19
	v_mul_lo_u32 v143, v128, s19
	v_mul_lo_u32 v145, v130, s19
	s_movk_i32 s19, 0xa0
	s_addc_u32 s15, s17, 0
	v_sub_u32_e32 v49, v196, v120
	v_and_b32_e32 v51, 24, v51
	v_lshlrev_b32_e32 v140, 4, v57
	v_lshlrev_b32_e32 v142, 4, v59
	v_lshlrev_b32_e32 v144, 4, v61
	v_lshlrev_b32_e32 v146, 4, v63
	v_sub_u32_e32 v52, v129, v56
	v_sub_u32_e32 v53, v141, v58
	v_sub_u32_e32 v54, v143, v60
	v_sub_u32_e32 v56, v145, v62
	v_mul_u32_u24_e32 v55, 0x120, v55
	v_mul_lo_u32 v48, v48, s19
	v_mul_u32_u24_e32 v50, 0x110, v50
	v_mov_b32_e32 v104, v197
	v_mov_b32_e32 v105, v197
	v_mov_b32_e32 v106, v197
	v_mov_b32_e32 v107, v197
	s_add_u32 s16, s3, 0x1000
	v_add_u32_e32 v147, v52, v140
	v_add_u32_e32 v148, v53, v142
	v_add_u32_e32 v149, v54, v144
	v_add_u32_e32 v150, v56, v146
	v_add_u32_e32 v151, v196, v48
	v_add_u32_e32 v152, v51, v50
	v_add_u32_e32 v153, v196, v55
	v_add_u32_e32 v154, v49, v48
	v_mov_b64_e32 v[60:61], v[104:105]
	v_mov_b64_e32 v[72:73], v[104:105]
	v_mov_b64_e32 v[64:65], v[104:105]
	v_mov_b64_e32 v[48:49], v[104:105]
	v_mov_b64_e32 v[56:57], v[104:105]
	v_mov_b64_e32 v[88:89], v[104:105]
	v_mov_b64_e32 v[92:93], v[104:105]
	v_mov_b64_e32 v[110:111], v[106:107]
	v_mov_b64_e32 v[76:77], v[104:105]
	v_mov_b64_e32 v[84:85], v[104:105]
	v_mov_b64_e32 v[80:81], v[104:105]
	v_mov_b64_e32 v[52:53], v[104:105]
	v_mov_b64_e32 v[68:69], v[104:105]
	v_mov_b64_e32 v[100:101], v[104:105]
	v_mov_b64_e32 v[96:97], v[104:105]
	s_addc_u32 s17, s17, 0
	v_ashrrev_i32_e32 v123, 31, v122
	s_or_b32 s3, s18, s2
	s_sub_i32 s25, 1, s2
	s_add_i32 s26, s18, s2
	s_mov_b32 s28, 0
	v_mov_b32_e32 v155, 0xf149f2ca
	v_mov_b32_e32 v131, 0
	v_mov_b64_e32 v[62:63], v[106:107]
	v_mov_b64_e32 v[74:75], v[106:107]
	v_mov_b64_e32 v[66:67], v[106:107]
	v_mov_b64_e32 v[50:51], v[106:107]
	v_mov_b64_e32 v[58:59], v[106:107]
	v_mov_b64_e32 v[90:91], v[106:107]
	v_mov_b64_e32 v[94:95], v[106:107]
	v_mov_b64_e32 v[108:109], v[104:105]
	v_mov_b64_e32 v[78:79], v[106:107]
	v_mov_b64_e32 v[86:87], v[106:107]
	v_mov_b64_e32 v[82:83], v[106:107]
	v_mov_b64_e32 v[54:55], v[106:107]
	v_mov_b64_e32 v[70:71], v[106:107]
	v_mov_b64_e32 v[102:103], v[106:107]
	v_mov_b64_e32 v[98:99], v[106:107]
	v_mov_b32_e32 v121, 0
	v_mov_b32_e32 v156, 0xf149f2ca
	v_mul_lo_u32 v242, v124, s10
	v_mul_lo_u32 v243, v126, s10
	v_mul_lo_u32 v244, v128, s10
	v_mul_lo_u32 v245, v130, s10
	s_movk_i32 s34, 0xc00
	v_mul_lo_u32 v246, v124, s34
	v_mul_lo_u32 v247, v126, s34
	v_mul_lo_u32 v248, v128, s34
	v_mul_lo_u32 v249, v130, s34
	v_lshl_add_u32 v242, v242, 1, v138
	v_lshl_add_u32 v243, v243, 1, v136
	v_lshl_add_u32 v244, v244, 1, v134
	v_lshl_add_u32 v245, v245, 1, v132
	v_lshl_add_u32 v246, v246, 1, v138
	v_lshl_add_u32 v247, v247, 1, v136
	v_lshl_add_u32 v248, v248, 1, v134
	v_lshl_add_u32 v249, v249, 1, v132
	v_add_u32_e32 v238, v129, v140
	v_add_u32_e32 v239, v141, v142
	v_add_u32_e32 v240, v143, v144
	v_add_u32_e32 v241, v145, v146
	v_bfe_u32 v214, v228, 4, 2
	v_mul_u32_u24_e32 v214, 0x440, v214
	v_sub_u32_e32 v214, v152, v214
.LBB0_426:
	s_mov_b32 s32, 0x3e38aa3b
	s_barrier
	s_waitcnt vmcnt(0)
	ds_write_b128 v238, v[24:27]
	ds_write_b128 v239, v[28:31]
	s_add_i32 s27, s28, 1
	ds_write_b128 v240, v[40:43]
	s_cmp_ge_u32 s27, s3
	ds_write_b128 v241, v[44:47]
	ds_write_b128 v147, v[32:35] offset:18432
	ds_write_b128 v148, v[36:39] offset:18432
	ds_write_b128 v149, v[16:19] offset:18432
	ds_write_b128 v150, v[20:23] offset:18432
	s_waitcnt lgkmcnt(0)
	s_barrier
	s_cbranch_scc1 .LBB0_430
	s_cmp_lt_u32 s27, s2
	s_mov_b32 s29, s27
	s_mov_b64 s[18:19], s[10:11]
	s_mov_b64 s[22:23], s[6:7]
	s_mov_b64 s[20:21], s[8:9]
	s_cbranch_scc1 .LBB0_429
	s_add_i32 s29, s25, s28
	s_mov_b64 s[18:19], 0xc00
	s_mov_b64 s[22:23], s[14:15]
	s_mov_b64 s[20:21], s[16:17]
.LBB0_429:
	s_mul_hi_u32 s31, s29, s18
	s_mul_i32 s30, s29, s18
	s_lshl_b64 s[28:29], s[30:31], 7
	s_add_u32 s22, s22, s28
	s_addc_u32 s23, s23, s29
	s_add_u32 s20, s20, s28
	s_addc_u32 s21, s21, s29
	s_cmp_eq_u32 s18, s10
	s_cbranch_scc0 .Lattn_srcB
	global_load_dwordx4 v[24:27], v242, s[22:23]
	global_load_dwordx4 v[28:31], v243, s[22:23]
	global_load_dwordx4 v[40:43], v244, s[22:23]
	global_load_dwordx4 v[44:47], v245, s[22:23]
	global_load_dwordx4 v[32:35], v242, s[20:21]
	global_load_dwordx4 v[36:39], v243, s[20:21]
	global_load_dwordx4 v[16:19], v244, s[20:21]
	global_load_dwordx4 v[20:23], v245, s[20:21]
	s_branch .Lattn_ldone
.Lattn_srcB:
	global_load_dwordx4 v[24:27], v246, s[22:23]
	global_load_dwordx4 v[28:31], v247, s[22:23]
	global_load_dwordx4 v[40:43], v248, s[22:23]
	global_load_dwordx4 v[44:47], v249, s[22:23]
	global_load_dwordx4 v[32:35], v246, s[20:21]
	global_load_dwordx4 v[36:39], v247, s[20:21]
	global_load_dwordx4 v[16:19], v248, s[20:21]
	global_load_dwordx4 v[20:23], v249, s[20:21]
.Lattn_ldone:
	s_mov_b32 s30, 0xf149f2ca
.LBB0_430:
	ds_read_b128 v[158:161], v153 offset:4608
	ds_read_b128 v[162:165], v153 offset:4672
	ds_read_b128 v[112:115], v153
	ds_read_b128 v[116:119], v153 offset:64
	s_waitcnt lgkmcnt(3)
	v_mfma_f32_16x16x32_bf16 v[158:161], v[158:161], v[0:3], 0
	ds_read_b128 v[168:171], v153 offset:9280
	ds_read_b128 v[174:177], v153 offset:13888
	s_waitcnt lgkmcnt(4)
	v_mfma_f32_16x16x32_bf16 v[160:163], v[162:165], v[4:7], v[158:161]
	ds_read_b128 v[164:167], v153 offset:9216
	s_waitcnt lgkmcnt(0)
	v_mfma_f32_16x16x32_bf16 v[164:167], v[164:167], v[0:3], 0
	s_nop 4
	s_nop 0
	v_mfma_f32_16x16x32_bf16 v[166:169], v[168:171], v[4:7], v[164:167]
	ds_read_b128 v[170:173], v153 offset:13824
	v_mfma_f32_16x16x32_bf16 v[112:115], v[112:115], v[0:3], 0
	s_nop 0
	s_nop 0
	s_nop 3
	s_nop 0
	s_nop 0
	v_mfma_f32_16x16x32_bf16 v[114:117], v[116:119], v[4:7], v[112:115]
	s_nop 0
	s_waitcnt lgkmcnt(0)
	v_mfma_f32_16x16x32_bf16 v[170:173], v[170:173], v[0:3], 0
	v_mfma_f32_16x16x32_bf16 v[170:173], v[174:177], v[4:7], v[170:173]
	s_nop 7
	s_nop 1
	v_max3_f32 v194, v114, s30, v115
	v_max3_f32 v194, v194, v116, v117
	v_max3_f32 v194, v194, v160, v161
	v_max3_f32 v194, v194, v162, v163
	v_max3_f32 v194, v194, v166, v167
	v_max3_f32 v194, v194, v168, v169
	v_max3_f32 v194, v194, v170, v171
	v_max3_f32 v194, v194, v172, v173
	v_mov_b32_e32 v195, v194
	s_nop 1
	v_permlane16_swap_b32_e32 v194, v195
	v_max_f32_e32 v194, v194, v195
	v_mov_b32_e32 v195, v194
	s_nop 1
	v_permlane32_swap_b32_e32 v194, v195
	v_max_f32_e32 v194, v194, v195
	v_mul_f32_e32 v194, 0x3e38aa3b, v194
	v_max_f32_e32 v194, v155, v194
	v_pk_fma_f32 v[114:115], v[114:115], s[32:33], v[194:195] op_sel_hi:[1,0,0] neg_lo:[0,0,1] neg_hi:[0,0,1]
	v_pk_fma_f32 v[116:117], v[116:117], s[32:33], v[194:195] op_sel_hi:[1,0,0] neg_lo:[0,0,1] neg_hi:[0,0,1]
	v_pk_fma_f32 v[160:161], v[160:161], s[32:33], v[194:195] op_sel_hi:[1,0,0] neg_lo:[0,0,1] neg_hi:[0,0,1]
	v_pk_fma_f32 v[162:163], v[162:163], s[32:33], v[194:195] op_sel_hi:[1,0,0] neg_lo:[0,0,1] neg_hi:[0,0,1]
	v_pk_fma_f32 v[166:167], v[166:167], s[32:33], v[194:195] op_sel_hi:[1,0,0] neg_lo:[0,0,1] neg_hi:[0,0,1]
	v_pk_fma_f32 v[168:169], v[168:169], s[32:33], v[194:195] op_sel_hi:[1,0,0] neg_lo:[0,0,1] neg_hi:[0,0,1]
	v_pk_fma_f32 v[170:171], v[170:171], s[32:33], v[194:195] op_sel_hi:[1,0,0] neg_lo:[0,0,1] neg_hi:[0,0,1]
	v_pk_fma_f32 v[172:173], v[172:173], s[32:33], v[194:195] op_sel_hi:[1,0,0] neg_lo:[0,0,1] neg_hi:[0,0,1]
	v_cmp_gt_f32_e32 vcc, v194, v155
	s_cbranch_vccz .LBB0_432
	v_sub_f32_e32 v155, v155, v194
	v_exp_f32_e32 v215, v155
	v_mov_b32_e32 v155, v194
	v_mul_f32_e32 v131, v131, v215
	v_pk_mul_f32 v[98:99], v[98:99], v[214:215] op_sel:[0,1] op_sel_hi:[1,1]
	v_pk_mul_f32 v[96:97], v[96:97], v[214:215] op_sel:[0,1] op_sel_hi:[1,1]
	v_pk_mul_f32 v[102:103], v[102:103], v[214:215] op_sel:[0,1] op_sel_hi:[1,1]
	v_pk_mul_f32 v[100:101], v[100:101], v[214:215] op_sel:[0,1] op_sel_hi:[1,1]
	v_pk_mul_f32 v[70:71], v[70:71], v[214:215] op_sel:[0,1] op_sel_hi:[1,1]
	v_pk_mul_f32 v[68:69], v[68:69], v[214:215] op_sel:[0,1] op_sel_hi:[1,1]
	v_pk_mul_f32 v[54:55], v[54:55], v[214:215] op_sel:[0,1] op_sel_hi:[1,1]
	v_pk_mul_f32 v[52:53], v[52:53], v[214:215] op_sel:[0,1] op_sel_hi:[1,1]
	v_pk_mul_f32 v[82:83], v[82:83], v[214:215] op_sel:[0,1] op_sel_hi:[1,1]
	v_pk_mul_f32 v[80:81], v[80:81], v[214:215] op_sel:[0,1] op_sel_hi:[1,1]
	v_pk_mul_f32 v[86:87], v[86:87], v[214:215] op_sel:[0,1] op_sel_hi:[1,1]
	v_pk_mul_f32 v[84:85], v[84:85], v[214:215] op_sel:[0,1] op_sel_hi:[1,1]
	v_pk_mul_f32 v[78:79], v[78:79], v[214:215] op_sel:[0,1] op_sel_hi:[1,1]
	v_pk_mul_f32 v[76:77], v[76:77], v[214:215] op_sel:[0,1] op_sel_hi:[1,1]
	v_pk_mul_f32 v[110:111], v[110:111], v[214:215] op_sel:[0,1] op_sel_hi:[1,1]
	v_pk_mul_f32 v[108:109], v[108:109], v[214:215] op_sel:[0,1] op_sel_hi:[1,1]
.LBB0_432:
	v_exp_f32_e32 v114, v114
	v_exp_f32_e32 v115, v115
	v_exp_f32_e32 v116, v116
	v_exp_f32_e32 v117, v117
	v_exp_f32_e32 v160, v160
	v_exp_f32_e32 v161, v161
	v_exp_f32_e32 v162, v162
	v_exp_f32_e32 v163, v163
	v_exp_f32_e32 v166, v166
	v_exp_f32_e32 v167, v167
	v_exp_f32_e32 v168, v168
	v_exp_f32_e32 v169, v169
	v_exp_f32_e32 v170, v170
	v_exp_f32_e32 v171, v171
	v_exp_f32_e32 v172, v172
	v_exp_f32_e32 v173, v173
	s_nop 0
	v_cvt_pk_bf16_f32 v216, v114, v115
	v_cvt_pk_bf16_f32 v218, v160, v161
	v_cvt_pk_bf16_f32 v220, v166, v167
	v_cvt_pk_bf16_f32 v222, v170, v171
	v_pk_add_f32 v[114:115], v[114:115], v[116:117]
	v_pk_add_f32 v[160:161], v[160:161], v[162:163]
	v_pk_add_f32 v[166:167], v[166:167], v[168:169]
	v_pk_add_f32 v[170:171], v[170:171], v[172:173]
	v_pk_add_f32 v[114:115], v[114:115], v[160:161]
	v_pk_add_f32 v[170:171], v[170:171], v[166:167]
	v_cvt_pk_bf16_f32 v217, v116, v117
	v_pk_add_f32 v[170:171], v[170:171], v[114:115]
	v_cvt_pk_bf16_f32 v219, v162, v163
	v_add_f32_e32 v170, v170, v171
	v_cvt_pk_bf16_f32 v221, v168, v169
	v_add_f32_e32 v131, v170, v131
	v_cvt_pk_bf16_f32 v223, v172, v173
	ds_read_b128 v[112:115], v153 offset:128
	ds_read_b128 v[116:119], v153 offset:192
	s_waitcnt lgkmcnt(1)
	v_mfma_f32_16x16x32_bf16 v[112:115], v[112:115], v[8:11], 0
	ds_read_b128 v[158:161], v153 offset:4736
	ds_read_b128 v[162:165], v153 offset:9344
	ds_read_b128 v[182:185], v153 offset:13952
	s_waitcnt lgkmcnt(3)
	v_mfma_f32_16x16x32_bf16 v[112:115], v[116:119], v[12:15], v[112:115]
	ds_read_b128 v[116:119], v153 offset:4800
	s_waitcnt lgkmcnt(3)
	v_mfma_f32_16x16x32_bf16 v[158:161], v[158:161], v[8:11], 0
	s_waitcnt lgkmcnt(0)
	v_mfma_f32_16x16x32_bf16 v[116:119], v[116:119], v[12:15], v[158:161]
	s_nop 5
	ds_read_b128 v[158:161], v153 offset:9408
	v_mfma_f32_16x16x32_bf16 v[162:165], v[162:165], v[8:11], 0
	s_waitcnt lgkmcnt(0)
	v_mfma_f32_16x16x32_bf16 v[186:189], v[158:161], v[12:15], v[162:165]
	ds_read_b128 v[158:161], v153 offset:14016
	s_nop 6
	s_nop 0
	v_mfma_f32_16x16x32_bf16 v[162:165], v[182:185], v[8:11], 0
	s_waitcnt lgkmcnt(0)
	v_mfma_f32_16x16x32_bf16 v[182:185], v[158:161], v[12:15], v[162:165]
	s_nop 7
	s_nop 1
	v_max3_f32 v194, v112, s30, v113
	v_max3_f32 v194, v194, v114, v115
	v_max3_f32 v194, v194, v116, v117
	v_max3_f32 v194, v194, v118, v119
	v_max3_f32 v194, v194, v186, v187
	v_max3_f32 v194, v194, v188, v189
	v_max3_f32 v194, v194, v182, v183
	v_max3_f32 v194, v194, v184, v185
	v_mov_b32_e32 v195, v194
	s_nop 1
	v_permlane16_swap_b32_e32 v194, v195
	v_max_f32_e32 v194, v194, v195
	v_mov_b32_e32 v195, v194
	s_nop 1
	v_permlane32_swap_b32_e32 v194, v195
	v_max_f32_e32 v194, v194, v195
	v_mul_f32_e32 v194, 0x3e38aa3b, v194
	v_max_f32_e32 v194, v156, v194
	v_pk_fma_f32 v[112:113], v[112:113], s[32:33], v[194:195] op_sel_hi:[1,0,0] neg_lo:[0,0,1] neg_hi:[0,0,1]
	v_pk_fma_f32 v[114:115], v[114:115], s[32:33], v[194:195] op_sel_hi:[1,0,0] neg_lo:[0,0,1] neg_hi:[0,0,1]
	v_pk_fma_f32 v[116:117], v[116:117], s[32:33], v[194:195] op_sel_hi:[1,0,0] neg_lo:[0,0,1] neg_hi:[0,0,1]
	v_pk_fma_f32 v[118:119], v[118:119], s[32:33], v[194:195] op_sel_hi:[1,0,0] neg_lo:[0,0,1] neg_hi:[0,0,1]
	v_pk_fma_f32 v[186:187], v[186:187], s[32:33], v[194:195] op_sel_hi:[1,0,0] neg_lo:[0,0,1] neg_hi:[0,0,1]
	v_pk_fma_f32 v[188:189], v[188:189], s[32:33], v[194:195] op_sel_hi:[1,0,0] neg_lo:[0,0,1] neg_hi:[0,0,1]
	v_pk_fma_f32 v[182:183], v[182:183], s[32:33], v[194:195] op_sel_hi:[1,0,0] neg_lo:[0,0,1] neg_hi:[0,0,1]
	v_pk_fma_f32 v[184:185], v[184:185], s[32:33], v[194:195] op_sel_hi:[1,0,0] neg_lo:[0,0,1] neg_hi:[0,0,1]
	v_cmp_gt_f32_e32 vcc, v194, v156
	s_cbranch_vccz .LBB0_434
	v_sub_f32_e32 v156, v156, v194
	v_exp_f32_e32 v156, v156
	s_nop 0
	v_mul_f32_e32 v121, v121, v156
	v_pk_mul_f32 v[94:95], v[94:95], v[156:157] op_sel_hi:[1,0]
	v_pk_mul_f32 v[92:93], v[92:93], v[156:157] op_sel_hi:[1,0]
	v_pk_mul_f32 v[90:91], v[90:91], v[156:157] op_sel_hi:[1,0]
	v_pk_mul_f32 v[88:89], v[88:89], v[156:157] op_sel_hi:[1,0]
	v_pk_mul_f32 v[58:59], v[58:59], v[156:157] op_sel_hi:[1,0]
	v_pk_mul_f32 v[56:57], v[56:57], v[156:157] op_sel_hi:[1,0]
	v_pk_mul_f32 v[50:51], v[50:51], v[156:157] op_sel_hi:[1,0]
	v_pk_mul_f32 v[48:49], v[48:49], v[156:157] op_sel_hi:[1,0]
	v_pk_mul_f32 v[66:67], v[66:67], v[156:157] op_sel_hi:[1,0]
	v_pk_mul_f32 v[64:65], v[64:65], v[156:157] op_sel_hi:[1,0]
	v_pk_mul_f32 v[74:75], v[74:75], v[156:157] op_sel_hi:[1,0]
	v_pk_mul_f32 v[72:73], v[72:73], v[156:157] op_sel_hi:[1,0]
	v_pk_mul_f32 v[62:63], v[62:63], v[156:157] op_sel_hi:[1,0]
	v_pk_mul_f32 v[60:61], v[60:61], v[156:157] op_sel_hi:[1,0]
	v_pk_mul_f32 v[106:107], v[106:107], v[156:157] op_sel_hi:[1,0]
	v_pk_mul_f32 v[104:105], v[104:105], v[156:157] op_sel_hi:[1,0]
	v_mov_b32_e32 v156, v194
.LBB0_434:
	v_exp_f32_e32 v112, v112
	v_exp_f32_e32 v113, v113
	v_exp_f32_e32 v114, v114
	v_exp_f32_e32 v115, v115
	v_exp_f32_e32 v116, v116
	v_exp_f32_e32 v117, v117
	v_exp_f32_e32 v118, v118
	v_exp_f32_e32 v119, v119
	v_exp_f32_e32 v186, v186
	v_exp_f32_e32 v187, v187
	v_exp_f32_e32 v188, v188
	v_exp_f32_e32 v189, v189
	v_exp_f32_e32 v182, v182
	v_exp_f32_e32 v183, v183
	v_exp_f32_e32 v184, v184
	v_exp_f32_e32 v185, v185
	s_nop 0
	v_cvt_pk_bf16_f32 v224, v112, v113
	v_cvt_pk_bf16_f32 v226, v116, v117
	v_cvt_pk_bf16_f32 v230, v186, v187
	v_cvt_pk_bf16_f32 v232, v182, v183
	v_pk_add_f32 v[112:113], v[112:113], v[114:115]
	v_pk_add_f32 v[116:117], v[116:117], v[118:119]
	v_pk_add_f32 v[186:187], v[186:187], v[188:189]
	v_pk_add_f32 v[182:183], v[182:183], v[184:185]
	v_pk_add_f32 v[112:113], v[112:113], v[116:117]
	v_pk_add_f32 v[182:183], v[182:183], v[186:187]
	v_cvt_pk_bf16_f32 v225, v114, v115
	v_pk_add_f32 v[182:183], v[182:183], v[112:113]
	v_cvt_pk_bf16_f32 v227, v118, v119
	v_add_f32_e32 v182, v182, v183
	v_cvt_pk_bf16_f32 v231, v188, v189
	v_add_f32_e32 v121, v182, v121
	v_cvt_pk_bf16_f32 v233, v184, v185
	s_cmp_lg_u32 s26, s27
	ds_read_b64_tr_b16 v[198:199], v214 offset:18432
	ds_read_b64_tr_b16 v[200:201], v214 offset:22784
	ds_read_b64_tr_b16 v[202:203], v214 offset:18464
	ds_read_b64_tr_b16 v[204:205], v214 offset:22816
	ds_read_b64_tr_b16 v[206:207], v214 offset:18496
	ds_read_b64_tr_b16 v[208:209], v214 offset:22848
	ds_read_b64_tr_b16 v[210:211], v214 offset:18528
	ds_read_b64_tr_b16 v[212:213], v214 offset:22880
	s_waitcnt lgkmcnt(6)
	v_mfma_f32_16x16x32_bf16 v[96:99], v[198:201], v[216:219], v[96:99]
	v_mfma_f32_16x16x32_bf16 v[92:95], v[198:201], v[224:227], v[92:95]
	ds_read_b64_tr_b16 v[198:199], v214 offset:18560
	ds_read_b64_tr_b16 v[200:201], v214 offset:22912
	s_waitcnt lgkmcnt(6)
	v_mfma_f32_16x16x32_bf16 v[100:103], v[202:205], v[216:219], v[100:103]
	v_mfma_f32_16x16x32_bf16 v[88:91], v[202:205], v[224:227], v[88:91]
	ds_read_b64_tr_b16 v[202:203], v214 offset:18592
	ds_read_b64_tr_b16 v[204:205], v214 offset:22944
	s_waitcnt lgkmcnt(6)
	v_mfma_f32_16x16x32_bf16 v[68:71], v[206:209], v[216:219], v[68:71]
	v_mfma_f32_16x16x32_bf16 v[56:59], v[206:209], v[224:227], v[56:59]
	ds_read_b64_tr_b16 v[206:207], v214 offset:18624
	ds_read_b64_tr_b16 v[208:209], v214 offset:22976
	s_waitcnt lgkmcnt(6)
	v_mfma_f32_16x16x32_bf16 v[52:55], v[210:213], v[216:219], v[52:55]
	v_mfma_f32_16x16x32_bf16 v[48:51], v[210:213], v[224:227], v[48:51]
	ds_read_b64_tr_b16 v[210:211], v214 offset:18656
	ds_read_b64_tr_b16 v[212:213], v214 offset:23008
	s_waitcnt lgkmcnt(6)
	v_mfma_f32_16x16x32_bf16 v[80:83], v[198:201], v[216:219], v[80:83]
	v_mfma_f32_16x16x32_bf16 v[64:67], v[198:201], v[224:227], v[64:67]
	ds_read_b64_tr_b16 v[198:199], v214 offset:27136
	ds_read_b64_tr_b16 v[200:201], v214 offset:31488
	s_waitcnt lgkmcnt(6)
	v_mfma_f32_16x16x32_bf16 v[84:87], v[202:205], v[216:219], v[84:87]
	v_mfma_f32_16x16x32_bf16 v[72:75], v[202:205], v[224:227], v[72:75]
	ds_read_b64_tr_b16 v[202:203], v214 offset:27168
	ds_read_b64_tr_b16 v[204:205], v214 offset:31520
	s_waitcnt lgkmcnt(6)
	v_mfma_f32_16x16x32_bf16 v[76:79], v[206:209], v[216:219], v[76:79]
	v_mfma_f32_16x16x32_bf16 v[60:63], v[206:209], v[224:227], v[60:63]
	ds_read_b64_tr_b16 v[206:207], v214 offset:27200
	ds_read_b64_tr_b16 v[208:209], v214 offset:31552
	s_waitcnt lgkmcnt(6)
	v_mfma_f32_16x16x32_bf16 v[108:111], v[210:213], v[216:219], v[108:111]
	v_mfma_f32_16x16x32_bf16 v[104:107], v[210:213], v[224:227], v[104:107]
	ds_read_b64_tr_b16 v[210:211], v214 offset:27232
	ds_read_b64_tr_b16 v[212:213], v214 offset:31584
	s_waitcnt lgkmcnt(6)
	v_mfma_f32_16x16x32_bf16 v[96:99], v[198:201], v[220:223], v[96:99]
	v_mfma_f32_16x16x32_bf16 v[92:95], v[198:201], v[230:233], v[92:95]
	ds_read_b64_tr_b16 v[198:199], v214 offset:27264
	ds_read_b64_tr_b16 v[200:201], v214 offset:31616
	s_waitcnt lgkmcnt(6)
	v_mfma_f32_16x16x32_bf16 v[100:103], v[202:205], v[220:223], v[100:103]
	v_mfma_f32_16x16x32_bf16 v[88:91], v[202:205], v[230:233], v[88:91]
	ds_read_b64_tr_b16 v[202:203], v214 offset:27296
	ds_read_b64_tr_b16 v[204:205], v214 offset:31648
	s_waitcnt lgkmcnt(6)
	v_mfma_f32_16x16x32_bf16 v[68:71], v[206:209], v[220:223], v[68:71]
	v_mfma_f32_16x16x32_bf16 v[56:59], v[206:209], v[230:233], v[56:59]
	ds_read_b64_tr_b16 v[206:207], v214 offset:27328
	ds_read_b64_tr_b16 v[208:209], v214 offset:31680
	s_waitcnt lgkmcnt(6)
	v_mfma_f32_16x16x32_bf16 v[52:55], v[210:213], v[220:223], v[52:55]
	v_mfma_f32_16x16x32_bf16 v[48:51], v[210:213], v[230:233], v[48:51]
	ds_read_b64_tr_b16 v[210:211], v214 offset:27360
	ds_read_b64_tr_b16 v[212:213], v214 offset:31712
	s_waitcnt lgkmcnt(6)
	v_mfma_f32_16x16x32_bf16 v[80:83], v[198:201], v[220:223], v[80:83]
	v_mfma_f32_16x16x32_bf16 v[64:67], v[198:201], v[230:233], v[64:67]
	s_waitcnt lgkmcnt(4)
	v_mfma_f32_16x16x32_bf16 v[84:87], v[202:205], v[220:223], v[84:87]
	v_mfma_f32_16x16x32_bf16 v[72:75], v[202:205], v[230:233], v[72:75]
	s_waitcnt lgkmcnt(2)
	v_mfma_f32_16x16x32_bf16 v[76:79], v[206:209], v[220:223], v[76:79]
	v_mfma_f32_16x16x32_bf16 v[60:63], v[206:209], v[230:233], v[60:63]
	s_waitcnt lgkmcnt(0)
	v_mfma_f32_16x16x32_bf16 v[108:111], v[210:213], v[220:223], v[108:111]
	v_mfma_f32_16x16x32_bf16 v[104:107], v[210:213], v[230:233], v[104:107]
	s_cbranch_scc0 .LBB0_419
	s_mov_b32 s28, s27
	s_branch .LBB0_426

.LBB0_662:
	v_or_b32_e32 v170, s50, v191
	s_movk_i32 s2, 0xf0
	v_and_or_b32 v0, v170, s2, v192
	v_lshlrev_b32_e32 v0, 12, v0
	v_mov_b32_e32 v1, v197
	v_lshl_add_u64 v[0:1], v[146:147], 0, v[0:1]
	v_mov_b32_e32 v149, v197
	v_lshl_add_u64 v[0:1], v[0:1], 0, v[148:149]
	s_mov_b32 s42, 0x9100000
	s_mov_b32 s43, 0
	v_lshl_add_u64 v[40:41], v[0:1], 0, s[42:43]
	global_load_dword v8, v[40:41], off
	global_load_dword v24, v[40:41], off offset:2048
	s_add_u32 s42, s42, 0x1000
	v_lshl_add_u64 v[42:43], v[0:1], 0, s[42:43]
	global_load_dword v9, v[42:43], off
	global_load_dword v25, v[42:43], off offset:2048
	s_add_u32 s42, s42, 0x1000
	v_lshl_add_u64 v[44:45], v[0:1], 0, s[42:43]
	global_load_dword v10, v[44:45], off
	global_load_dword v26, v[44:45], off offset:2048
	s_add_u32 s42, s42, 0x1000
	v_lshl_add_u64 v[46:47], v[0:1], 0, s[42:43]
	global_load_dword v11, v[46:47], off
	global_load_dword v27, v[46:47], off offset:2048
	s_add_u32 s42, s42, 0x1000
	v_lshl_add_u64 v[48:49], v[0:1], 0, s[42:43]
	global_load_dword v12, v[48:49], off
	global_load_dword v28, v[48:49], off offset:2048
	s_add_u32 s42, s42, 0x1000
	v_lshl_add_u64 v[50:51], v[0:1], 0, s[42:43]
	global_load_dword v13, v[50:51], off
	global_load_dword v29, v[50:51], off offset:2048
	s_add_u32 s42, s42, 0x1000
	v_lshl_add_u64 v[52:53], v[0:1], 0, s[42:43]
	global_load_dword v14, v[52:53], off
	global_load_dword v30, v[52:53], off offset:2048
	s_add_u32 s42, s42, 0x1000
	v_lshl_add_u64 v[54:55], v[0:1], 0, s[42:43]
	global_load_dword v15, v[54:55], off
	global_load_dword v31, v[54:55], off offset:2048
	s_add_u32 s42, s42, 0x1000
	v_lshl_add_u64 v[56:57], v[0:1], 0, s[42:43]
	global_load_dword v16, v[56:57], off
	global_load_dword v32, v[56:57], off offset:2048
	s_add_u32 s42, s42, 0x1000
	v_lshl_add_u64 v[58:59], v[0:1], 0, s[42:43]
	global_load_dword v17, v[58:59], off
	global_load_dword v33, v[58:59], off offset:2048
	s_add_u32 s42, s42, 0x1000
	v_lshl_add_u64 v[60:61], v[0:1], 0, s[42:43]
	global_load_dword v18, v[60:61], off
	global_load_dword v34, v[60:61], off offset:2048
	s_add_u32 s42, s42, 0x1000
	v_lshl_add_u64 v[62:63], v[0:1], 0, s[42:43]
	global_load_dword v19, v[62:63], off
	global_load_dword v35, v[62:63], off offset:2048
	s_add_u32 s42, s42, 0x1000
	v_lshl_add_u64 v[64:65], v[0:1], 0, s[42:43]
	global_load_dword v20, v[64:65], off
	global_load_dword v36, v[64:65], off offset:2048
	s_add_u32 s42, s42, 0x1000
	v_lshl_add_u64 v[66:67], v[0:1], 0, s[42:43]
	global_load_dword v21, v[66:67], off
	global_load_dword v37, v[66:67], off offset:2048
	s_add_u32 s42, s42, 0x1000
	v_lshl_add_u64 v[68:69], v[0:1], 0, s[42:43]
	global_load_dword v22, v[68:69], off
	global_load_dword v38, v[68:69], off offset:2048
	s_add_u32 s42, s42, 0x1000
	v_lshl_add_u64 v[70:71], v[0:1], 0, s[42:43]
	global_load_dword v23, v[70:71], off
	global_load_dword v39, v[70:71], off offset:2048
	s_xor_b64 s[40:41], s[4:5], -1
	s_mov_b64 s[4:5], -1
	s_mov_b32 s2, 0
	v_or_b32_e32 v0, v170, v198
	v_ashrrev_i32_e32 v1, 31, v0
	v_lshlrev_b64 v[172:173], 12, v[0:1]
	s_waitcnt vmcnt(0)
	v_pk_add_f32 v[168:169], v[8:9], v[24:25]
	v_pk_add_f32 v[166:167], v[10:11], v[26:27]
	v_pk_add_f32 v[164:165], v[12:13], v[28:29]
	v_pk_add_f32 v[162:163], v[14:15], v[30:31]
	v_pk_add_f32 v[160:161], v[16:17], v[32:33]
	v_pk_add_f32 v[158:159], v[18:19], v[34:35]
	v_pk_add_f32 v[156:157], v[20:21], v[36:37]
	v_pk_add_f32 v[154:155], v[22:23], v[38:39]
	v_or_b32_e32 v2, 4, v0
	v_ashrrev_i32_e32 v3, 31, v2
	v_lshlrev_b64 v[174:175], 12, v[2:3]
	v_or_b32_e32 v2, 8, v0
	v_or_b32_e32 v0, 12, v0
	v_ashrrev_i32_e32 v3, 31, v2
	v_ashrrev_i32_e32 v1, 31, v0
	v_lshlrev_b64 v[176:177], 12, v[2:3]
	v_lshlrev_b64 v[178:179], 12, v[0:1]
	s_branch .LBB0_664

.LBB0_668:
	s_cmp_eq_u64 s[54:55], 0
	s_cbranch_scc1 .LBB0_663
	s_lshl_b32 s50, s2, 9
	v_lshl_add_u64 v[76:77], s[50:51], 2, v[142:143]
	v_lshl_add_u64 v[64:65], v[76:77], 0, v[172:173]
	global_load_dwordx4 v[44:47], v199, s[54:55] offset:48
	global_load_dwordx4 v[52:55], v199, s[54:55] offset:32
	global_load_dwordx4 v[56:59], v199, s[54:55] offset:16
	global_load_dwordx4 v[60:63], v199, s[54:55]
	global_load_dwordx4 v[32:35], v199, s[54:55] offset:112
	global_load_dwordx4 v[36:39], v199, s[54:55] offset:96
	global_load_dwordx4 v[40:43], v199, s[54:55] offset:80
	global_load_dwordx4 v[48:51], v199, s[54:55] offset:64
	global_load_dwordx4 v[16:19], v199, s[54:55] offset:176
	global_load_dwordx4 v[20:23], v199, s[54:55] offset:160
	global_load_dwordx4 v[24:27], v199, s[54:55] offset:144
	global_load_dwordx4 v[28:31], v199, s[54:55] offset:128
	global_load_dwordx4 v[0:3], v199, s[54:55] offset:240
	global_load_dwordx4 v[4:7], v199, s[54:55] offset:224
	global_load_dwordx4 v[8:11], v199, s[54:55] offset:208
	global_load_dwordx4 v[12:15], v199, s[54:55] offset:192
	v_lshl_add_u64 v[68:69], v[76:77], 0, v[174:175]
	global_load_dwordx4 v[64:67], v[64:65], off
	v_lshl_add_u64 v[72:73], v[76:77], 0, v[176:177]
	global_load_dwordx4 v[68:71], v[68:69], off
	v_lshl_add_u64 v[76:77], v[76:77], 0, v[178:179]
	global_load_dwordx4 v[72:75], v[72:73], off
	s_waitcnt vmcnt(15)
	v_mov_b32_e32 v180, v63
	global_load_dwordx4 v[76:79], v[76:77], off
	s_waitcnt vmcnt(3)
	ds_write_b128 v193, v[64:67]
	s_waitcnt vmcnt(2)
	ds_write_b128 v193, v[68:71] offset:1024
	s_waitcnt vmcnt(1)
	ds_write_b128 v193, v[72:75] offset:2048
	s_waitcnt vmcnt(0)
	ds_write_b128 v193, v[76:79] offset:3072
	ds_read_b128 v[64:67], v190
	ds_read_b128 v[68:71], v190 offset:16
	ds_read_b128 v[72:75], v190 offset:32
	ds_read_b128 v[76:79], v190 offset:48
	ds_read_b128 v[80:83], v190 offset:64
	ds_read_b128 v[84:87], v190 offset:80
	ds_read_b128 v[88:91], v190 offset:96
	ds_read_b128 v[92:95], v190 offset:112
	ds_read_b128 v[96:99], v190 offset:128
	ds_read_b128 v[100:103], v190 offset:144
	ds_read_b128 v[104:107], v190 offset:160
	ds_read_b128 v[108:111], v190 offset:176
	s_waitcnt lgkmcnt(8)
	ds_read_b128 v[112:115], v190 offset:192
	ds_read_b128 v[116:119], v190 offset:208
	ds_read_b128 v[120:123], v190 offset:224
	ds_read_b128 v[124:127], v190 offset:240
	v_pk_mul_f32 v[128:129], v[60:61], v[64:65]
	v_pk_mul_f32 v[130:131], v[62:63], v[66:67]
	v_pk_fma_f32 v[128:129], v[56:57], v[68:69], v[128:129]
	v_pk_fma_f32 v[130:131], v[58:59], v[70:71], v[130:131]
	v_pk_fma_f32 v[128:129], v[52:53], v[72:73], v[128:129]
	v_pk_fma_f32 v[130:131], v[54:55], v[74:75], v[130:131]
	v_pk_fma_f32 v[128:129], v[44:45], v[76:77], v[128:129]
	v_pk_fma_f32 v[130:131], v[46:47], v[78:79], v[130:131]
	s_waitcnt lgkmcnt(8)
	ds_read_b128 v[64:67], v190 offset:256
	ds_read_b128 v[68:71], v190 offset:272
	ds_read_b128 v[72:75], v190 offset:288
	ds_read_b128 v[76:79], v190 offset:304
	v_pk_fma_f32 v[128:129], v[48:49], v[80:81], v[128:129]
	v_pk_fma_f32 v[130:131], v[50:51], v[82:83], v[130:131]
	v_pk_fma_f32 v[128:129], v[40:41], v[84:85], v[128:129]
	v_pk_fma_f32 v[130:131], v[42:43], v[86:87], v[130:131]
	v_pk_fma_f32 v[128:129], v[36:37], v[88:89], v[128:129]
	v_pk_fma_f32 v[130:131], v[38:39], v[90:91], v[130:131]
	v_pk_fma_f32 v[128:129], v[32:33], v[92:93], v[128:129]
	v_pk_fma_f32 v[130:131], v[34:35], v[94:95], v[130:131]
	s_waitcnt lgkmcnt(8)
	ds_read_b128 v[80:83], v190 offset:320
	ds_read_b128 v[84:87], v190 offset:336
	ds_read_b128 v[88:91], v190 offset:352
	ds_read_b128 v[92:95], v190 offset:368
	v_pk_fma_f32 v[128:129], v[28:29], v[96:97], v[128:129]
	v_pk_fma_f32 v[130:131], v[30:31], v[98:99], v[130:131]
	v_pk_fma_f32 v[128:129], v[24:25], v[100:101], v[128:129]
	v_pk_fma_f32 v[130:131], v[26:27], v[102:103], v[130:131]
	v_pk_fma_f32 v[128:129], v[20:21], v[104:105], v[128:129]
	v_pk_fma_f32 v[130:131], v[22:23], v[106:107], v[130:131]
	v_pk_fma_f32 v[128:129], v[16:17], v[108:109], v[128:129]
	v_pk_fma_f32 v[130:131], v[18:19], v[110:111], v[130:131]
	s_waitcnt lgkmcnt(8)
	ds_read_b128 v[96:99], v190 offset:384
	ds_read_b128 v[100:103], v190 offset:400
	ds_read_b128 v[104:107], v190 offset:416
	ds_read_b128 v[108:111], v190 offset:432
	v_pk_fma_f32 v[128:129], v[12:13], v[112:113], v[128:129]
	v_pk_fma_f32 v[130:131], v[14:15], v[114:115], v[130:131]
	v_pk_fma_f32 v[128:129], v[8:9], v[116:117], v[128:129]
	v_pk_fma_f32 v[130:131], v[10:11], v[118:119], v[130:131]
	v_pk_fma_f32 v[128:129], v[4:5], v[120:121], v[128:129]
	v_pk_fma_f32 v[130:131], v[6:7], v[122:123], v[130:131]
	v_pk_fma_f32 v[128:129], v[0:1], v[124:125], v[128:129]
	v_pk_fma_f32 v[130:131], v[2:3], v[126:127], v[130:131]
	s_waitcnt lgkmcnt(8)
	ds_read_b128 v[112:115], v190 offset:448
	ds_read_b128 v[116:119], v190 offset:464
	ds_read_b128 v[120:123], v190 offset:480
	ds_read_b128 v[124:127], v190 offset:496
	v_pk_mul_f32 v[132:133], v[60:61], v[64:65]
	v_pk_mul_f32 v[134:135], v[62:63], v[66:67]
	v_pk_add_f32 v[128:129], v[128:129], v[130:131]
	v_pk_fma_f32 v[132:133], v[56:57], v[68:69], v[132:133]
	v_pk_fma_f32 v[134:135], v[58:59], v[70:71], v[134:135]
	v_add_f32_e32 v136, v128, v129
	v_pk_fma_f32 v[132:133], v[52:53], v[72:73], v[132:133]
	v_pk_fma_f32 v[134:135], v[54:55], v[74:75], v[134:135]
	v_add_f32_e32 v168, v168, v136
	v_pk_fma_f32 v[132:133], v[44:45], v[76:77], v[132:133]
	v_pk_fma_f32 v[134:135], v[46:47], v[78:79], v[134:135]
	s_waitcnt lgkmcnt(8)
	ds_read_b128 v[64:67], v190 offset:512
	ds_read_b128 v[68:71], v190 offset:528
	ds_read_b128 v[72:75], v190 offset:544
	ds_read_b128 v[76:79], v190 offset:560
	v_pk_fma_f32 v[132:133], v[48:49], v[80:81], v[132:133]
	v_pk_fma_f32 v[134:135], v[50:51], v[82:83], v[134:135]
	v_pk_fma_f32 v[132:133], v[40:41], v[84:85], v[132:133]
	v_pk_fma_f32 v[134:135], v[42:43], v[86:87], v[134:135]
	v_pk_fma_f32 v[132:133], v[36:37], v[88:89], v[132:133]
	v_pk_fma_f32 v[134:135], v[38:39], v[90:91], v[134:135]
	v_pk_fma_f32 v[132:133], v[32:33], v[92:93], v[132:133]
	v_pk_fma_f32 v[134:135], v[34:35], v[94:95], v[134:135]
	s_waitcnt lgkmcnt(8)
	ds_read_b128 v[80:83], v190 offset:576
	ds_read_b128 v[84:87], v190 offset:592
	ds_read_b128 v[88:91], v190 offset:608
	ds_read_b128 v[92:95], v190 offset:624
	v_pk_fma_f32 v[132:133], v[28:29], v[96:97], v[132:133]
	v_pk_fma_f32 v[134:135], v[30:31], v[98:99], v[134:135]
	v_pk_fma_f32 v[132:133], v[24:25], v[100:101], v[132:133]
	v_pk_fma_f32 v[134:135], v[26:27], v[102:103], v[134:135]
	v_pk_fma_f32 v[132:133], v[20:21], v[104:105], v[132:133]
	v_pk_fma_f32 v[134:135], v[22:23], v[106:107], v[134:135]
	v_pk_fma_f32 v[132:133], v[16:17], v[108:109], v[132:133]
	v_pk_fma_f32 v[134:135], v[18:19], v[110:111], v[134:135]
	s_waitcnt lgkmcnt(8)
	ds_read_b128 v[96:99], v190 offset:640
	ds_read_b128 v[100:103], v190 offset:656
	ds_read_b128 v[104:107], v190 offset:672
	ds_read_b128 v[108:111], v190 offset:688
	v_pk_fma_f32 v[132:133], v[12:13], v[112:113], v[132:133]
	v_pk_fma_f32 v[134:135], v[14:15], v[114:115], v[134:135]
	v_pk_fma_f32 v[132:133], v[8:9], v[116:117], v[132:133]
	v_pk_fma_f32 v[134:135], v[10:11], v[118:119], v[134:135]
	v_pk_fma_f32 v[132:133], v[4:5], v[120:121], v[132:133]
	v_pk_fma_f32 v[134:135], v[6:7], v[122:123], v[134:135]
	v_pk_fma_f32 v[132:133], v[0:1], v[124:125], v[132:133]
	v_pk_fma_f32 v[134:135], v[2:3], v[126:127], v[134:135]
	s_waitcnt lgkmcnt(8)
	ds_read_b128 v[112:115], v190 offset:704
	ds_read_b128 v[116:119], v190 offset:720
	ds_read_b128 v[120:123], v190 offset:736
	ds_read_b128 v[124:127], v190 offset:752
	v_pk_mul_f32 v[128:129], v[60:61], v[64:65]
	v_pk_mul_f32 v[130:131], v[62:63], v[66:67]
	v_pk_add_f32 v[132:133], v[132:133], v[134:135]
	v_pk_fma_f32 v[128:129], v[56:57], v[68:69], v[128:129]
	v_pk_fma_f32 v[130:131], v[58:59], v[70:71], v[130:131]
	v_add_f32_e32 v136, v132, v133
	v_pk_fma_f32 v[128:129], v[52:53], v[72:73], v[128:129]
	v_pk_fma_f32 v[130:131], v[54:55], v[74:75], v[130:131]
	v_add_f32_e32 v169, v169, v136
	v_pk_fma_f32 v[128:129], v[44:45], v[76:77], v[128:129]
	v_pk_fma_f32 v[130:131], v[46:47], v[78:79], v[130:131]
	s_waitcnt lgkmcnt(8)
	ds_read_b128 v[64:67], v190 offset:768
	ds_read_b128 v[68:71], v190 offset:784
	ds_read_b128 v[72:75], v190 offset:800
	ds_read_b128 v[76:79], v190 offset:816
	v_pk_fma_f32 v[128:129], v[48:49], v[80:81], v[128:129]
	v_pk_fma_f32 v[130:131], v[50:51], v[82:83], v[130:131]
	v_pk_fma_f32 v[128:129], v[40:41], v[84:85], v[128:129]
	v_pk_fma_f32 v[130:131], v[42:43], v[86:87], v[130:131]
	v_pk_fma_f32 v[128:129], v[36:37], v[88:89], v[128:129]
	v_pk_fma_f32 v[130:131], v[38:39], v[90:91], v[130:131]
	v_pk_fma_f32 v[128:129], v[32:33], v[92:93], v[128:129]
	v_pk_fma_f32 v[130:131], v[34:35], v[94:95], v[130:131]
	s_waitcnt lgkmcnt(8)
	ds_read_b128 v[80:83], v190 offset:832
	ds_read_b128 v[84:87], v190 offset:848
	ds_read_b128 v[88:91], v190 offset:864
	ds_read_b128 v[92:95], v190 offset:880
	v_pk_fma_f32 v[128:129], v[28:29], v[96:97], v[128:129]
	v_pk_fma_f32 v[130:131], v[30:31], v[98:99], v[130:131]
	v_pk_fma_f32 v[128:129], v[24:25], v[100:101], v[128:129]
	v_pk_fma_f32 v[130:131], v[26:27], v[102:103], v[130:131]
	v_pk_fma_f32 v[128:129], v[20:21], v[104:105], v[128:129]
	v_pk_fma_f32 v[130:131], v[22:23], v[106:107], v[130:131]
	v_pk_fma_f32 v[128:129], v[16:17], v[108:109], v[128:129]
	v_pk_fma_f32 v[130:131], v[18:19], v[110:111], v[130:131]
	s_waitcnt lgkmcnt(8)
	ds_read_b128 v[96:99], v190 offset:896
	ds_read_b128 v[100:103], v190 offset:912
	ds_read_b128 v[104:107], v190 offset:928
	ds_read_b128 v[108:111], v190 offset:944
	v_pk_fma_f32 v[128:129], v[12:13], v[112:113], v[128:129]
	v_pk_fma_f32 v[130:131], v[14:15], v[114:115], v[130:131]
	v_pk_fma_f32 v[128:129], v[8:9], v[116:117], v[128:129]
	v_pk_fma_f32 v[130:131], v[10:11], v[118:119], v[130:131]
	v_pk_fma_f32 v[128:129], v[4:5], v[120:121], v[128:129]
	v_pk_fma_f32 v[130:131], v[6:7], v[122:123], v[130:131]
	v_pk_fma_f32 v[128:129], v[0:1], v[124:125], v[128:129]
	v_pk_fma_f32 v[130:131], v[2:3], v[126:127], v[130:131]
	s_waitcnt lgkmcnt(8)
	ds_read_b128 v[112:115], v190 offset:960
	ds_read_b128 v[116:119], v190 offset:976
	ds_read_b128 v[120:123], v190 offset:992
	ds_read_b128 v[124:127], v190 offset:1008
	v_pk_mul_f32 v[132:133], v[60:61], v[64:65]
	v_pk_mul_f32 v[134:135], v[62:63], v[66:67]
	v_pk_add_f32 v[128:129], v[128:129], v[130:131]
	v_pk_fma_f32 v[132:133], v[56:57], v[68:69], v[132:133]
	v_pk_fma_f32 v[134:135], v[58:59], v[70:71], v[134:135]
	v_add_f32_e32 v136, v128, v129
	v_pk_fma_f32 v[132:133], v[52:53], v[72:73], v[132:133]
	v_pk_fma_f32 v[134:135], v[54:55], v[74:75], v[134:135]
	v_add_f32_e32 v166, v166, v136
	v_pk_fma_f32 v[132:133], v[44:45], v[76:77], v[132:133]
	v_pk_fma_f32 v[134:135], v[46:47], v[78:79], v[134:135]
	s_waitcnt lgkmcnt(8)
	ds_read_b128 v[64:67], v190 offset:1024
	ds_read_b128 v[68:71], v190 offset:1040
	ds_read_b128 v[72:75], v190 offset:1056
	ds_read_b128 v[76:79], v190 offset:1072
	v_pk_fma_f32 v[132:133], v[48:49], v[80:81], v[132:133]
	v_pk_fma_f32 v[134:135], v[50:51], v[82:83], v[134:135]
	v_pk_fma_f32 v[132:133], v[40:41], v[84:85], v[132:133]
	v_pk_fma_f32 v[134:135], v[42:43], v[86:87], v[134:135]
	v_pk_fma_f32 v[132:133], v[36:37], v[88:89], v[132:133]
	v_pk_fma_f32 v[134:135], v[38:39], v[90:91], v[134:135]
	v_pk_fma_f32 v[132:133], v[32:33], v[92:93], v[132:133]
	v_pk_fma_f32 v[134:135], v[34:35], v[94:95], v[134:135]
	s_waitcnt lgkmcnt(8)
	ds_read_b128 v[80:83], v190 offset:1088
	ds_read_b128 v[84:87], v190 offset:1104
	ds_read_b128 v[88:91], v190 offset:1120
	ds_read_b128 v[92:95], v190 offset:1136
	v_pk_fma_f32 v[132:133], v[28:29], v[96:97], v[132:133]
	v_pk_fma_f32 v[134:135], v[30:31], v[98:99], v[134:135]
	v_pk_fma_f32 v[132:133], v[24:25], v[100:101], v[132:133]
	v_pk_fma_f32 v[134:135], v[26:27], v[102:103], v[134:135]
	v_pk_fma_f32 v[132:133], v[20:21], v[104:105], v[132:133]
	v_pk_fma_f32 v[134:135], v[22:23], v[106:107], v[134:135]
	v_pk_fma_f32 v[132:133], v[16:17], v[108:109], v[132:133]
	v_pk_fma_f32 v[134:135], v[18:19], v[110:111], v[134:135]
	s_waitcnt lgkmcnt(8)
	ds_read_b128 v[96:99], v190 offset:1152
	ds_read_b128 v[100:103], v190 offset:1168
	ds_read_b128 v[104:107], v190 offset:1184
	ds_read_b128 v[108:111], v190 offset:1200
	v_pk_fma_f32 v[132:133], v[12:13], v[112:113], v[132:133]
	v_pk_fma_f32 v[134:135], v[14:15], v[114:115], v[134:135]
	v_pk_fma_f32 v[132:133], v[8:9], v[116:117], v[132:133]
	v_pk_fma_f32 v[134:135], v[10:11], v[118:119], v[134:135]
	v_pk_fma_f32 v[132:133], v[4:5], v[120:121], v[132:133]
	v_pk_fma_f32 v[134:135], v[6:7], v[122:123], v[134:135]
	v_pk_fma_f32 v[132:133], v[0:1], v[124:125], v[132:133]
	v_pk_fma_f32 v[134:135], v[2:3], v[126:127], v[134:135]
	s_waitcnt lgkmcnt(8)
	ds_read_b128 v[112:115], v190 offset:1216
	ds_read_b128 v[116:119], v190 offset:1232
	ds_read_b128 v[120:123], v190 offset:1248
	ds_read_b128 v[124:127], v190 offset:1264
	v_pk_mul_f32 v[128:129], v[60:61], v[64:65]
	v_pk_mul_f32 v[130:131], v[62:63], v[66:67]
	v_pk_add_f32 v[132:133], v[132:133], v[134:135]
	v_pk_fma_f32 v[128:129], v[56:57], v[68:69], v[128:129]
	v_pk_fma_f32 v[130:131], v[58:59], v[70:71], v[130:131]
	v_add_f32_e32 v136, v132, v133
	v_pk_fma_f32 v[128:129], v[52:53], v[72:73], v[128:129]
	v_pk_fma_f32 v[130:131], v[54:55], v[74:75], v[130:131]
	v_add_f32_e32 v167, v167, v136
	v_pk_fma_f32 v[128:129], v[44:45], v[76:77], v[128:129]
	v_pk_fma_f32 v[130:131], v[46:47], v[78:79], v[130:131]
	s_waitcnt lgkmcnt(8)
	ds_read_b128 v[64:67], v190 offset:1280
	ds_read_b128 v[68:71], v190 offset:1296
	ds_read_b128 v[72:75], v190 offset:1312
	ds_read_b128 v[76:79], v190 offset:1328
	v_pk_fma_f32 v[128:129], v[48:49], v[80:81], v[128:129]
	v_pk_fma_f32 v[130:131], v[50:51], v[82:83], v[130:131]
	v_pk_fma_f32 v[128:129], v[40:41], v[84:85], v[128:129]
	v_pk_fma_f32 v[130:131], v[42:43], v[86:87], v[130:131]
	v_pk_fma_f32 v[128:129], v[36:37], v[88:89], v[128:129]
	v_pk_fma_f32 v[130:131], v[38:39], v[90:91], v[130:131]
	v_pk_fma_f32 v[128:129], v[32:33], v[92:93], v[128:129]
	v_pk_fma_f32 v[130:131], v[34:35], v[94:95], v[130:131]
	s_waitcnt lgkmcnt(8)
	ds_read_b128 v[80:83], v190 offset:1344
	ds_read_b128 v[84:87], v190 offset:1360
	ds_read_b128 v[88:91], v190 offset:1376
	ds_read_b128 v[92:95], v190 offset:1392
	v_pk_fma_f32 v[128:129], v[28:29], v[96:97], v[128:129]
	v_pk_fma_f32 v[130:131], v[30:31], v[98:99], v[130:131]
	v_pk_fma_f32 v[128:129], v[24:25], v[100:101], v[128:129]
	v_pk_fma_f32 v[130:131], v[26:27], v[102:103], v[130:131]
	v_pk_fma_f32 v[128:129], v[20:21], v[104:105], v[128:129]
	v_pk_fma_f32 v[130:131], v[22:23], v[106:107], v[130:131]
	v_pk_fma_f32 v[128:129], v[16:17], v[108:109], v[128:129]
	v_pk_fma_f32 v[130:131], v[18:19], v[110:111], v[130:131]
	s_waitcnt lgkmcnt(8)
	ds_read_b128 v[96:99], v190 offset:1408
	ds_read_b128 v[100:103], v190 offset:1424
	ds_read_b128 v[104:107], v190 offset:1440
	ds_read_b128 v[108:111], v190 offset:1456
	v_pk_fma_f32 v[128:129], v[12:13], v[112:113], v[128:129]
	v_pk_fma_f32 v[130:131], v[14:15], v[114:115], v[130:131]
	v_pk_fma_f32 v[128:129], v[8:9], v[116:117], v[128:129]
	v_pk_fma_f32 v[130:131], v[10:11], v[118:119], v[130:131]
	v_pk_fma_f32 v[128:129], v[4:5], v[120:121], v[128:129]
	v_pk_fma_f32 v[130:131], v[6:7], v[122:123], v[130:131]
	v_pk_fma_f32 v[128:129], v[0:1], v[124:125], v[128:129]
	v_pk_fma_f32 v[130:131], v[2:3], v[126:127], v[130:131]
	s_waitcnt lgkmcnt(8)
	ds_read_b128 v[112:115], v190 offset:1472
	ds_read_b128 v[116:119], v190 offset:1488
	ds_read_b128 v[120:123], v190 offset:1504
	ds_read_b128 v[124:127], v190 offset:1520
	v_pk_mul_f32 v[132:133], v[60:61], v[64:65]
	v_pk_mul_f32 v[134:135], v[62:63], v[66:67]
	v_pk_add_f32 v[128:129], v[128:129], v[130:131]
	v_pk_fma_f32 v[132:133], v[56:57], v[68:69], v[132:133]
	v_pk_fma_f32 v[134:135], v[58:59], v[70:71], v[134:135]
	v_add_f32_e32 v136, v128, v129
	v_pk_fma_f32 v[132:133], v[52:53], v[72:73], v[132:133]
	v_pk_fma_f32 v[134:135], v[54:55], v[74:75], v[134:135]
	v_add_f32_e32 v164, v164, v136
	v_pk_fma_f32 v[132:133], v[44:45], v[76:77], v[132:133]
	v_pk_fma_f32 v[134:135], v[46:47], v[78:79], v[134:135]
	s_waitcnt lgkmcnt(8)
	ds_read_b128 v[64:67], v190 offset:1536
	ds_read_b128 v[68:71], v190 offset:1552
	ds_read_b128 v[72:75], v190 offset:1568
	ds_read_b128 v[76:79], v190 offset:1584
	v_pk_fma_f32 v[132:133], v[48:49], v[80:81], v[132:133]
	v_pk_fma_f32 v[134:135], v[50:51], v[82:83], v[134:135]
	v_pk_fma_f32 v[132:133], v[40:41], v[84:85], v[132:133]
	v_pk_fma_f32 v[134:135], v[42:43], v[86:87], v[134:135]
	v_pk_fma_f32 v[132:133], v[36:37], v[88:89], v[132:133]
	v_pk_fma_f32 v[134:135], v[38:39], v[90:91], v[134:135]
	v_pk_fma_f32 v[132:133], v[32:33], v[92:93], v[132:133]
	v_pk_fma_f32 v[134:135], v[34:35], v[94:95], v[134:135]
	s_waitcnt lgkmcnt(8)
	ds_read_b128 v[80:83], v190 offset:1600
	ds_read_b128 v[84:87], v190 offset:1616
	ds_read_b128 v[88:91], v190 offset:1632
	ds_read_b128 v[92:95], v190 offset:1648
	v_pk_fma_f32 v[132:133], v[28:29], v[96:97], v[132:133]
	v_pk_fma_f32 v[134:135], v[30:31], v[98:99], v[134:135]
	v_pk_fma_f32 v[132:133], v[24:25], v[100:101], v[132:133]
	v_pk_fma_f32 v[134:135], v[26:27], v[102:103], v[134:135]
	v_pk_fma_f32 v[132:133], v[20:21], v[104:105], v[132:133]
	v_pk_fma_f32 v[134:135], v[22:23], v[106:107], v[134:135]
	v_pk_fma_f32 v[132:133], v[16:17], v[108:109], v[132:133]
	v_pk_fma_f32 v[134:135], v[18:19], v[110:111], v[134:135]
	s_waitcnt lgkmcnt(8)
	ds_read_b128 v[96:99], v190 offset:1664
	ds_read_b128 v[100:103], v190 offset:1680
	ds_read_b128 v[104:107], v190 offset:1696
	ds_read_b128 v[108:111], v190 offset:1712
	v_pk_fma_f32 v[132:133], v[12:13], v[112:113], v[132:133]
	v_pk_fma_f32 v[134:135], v[14:15], v[114:115], v[134:135]
	v_pk_fma_f32 v[132:133], v[8:9], v[116:117], v[132:133]
	v_pk_fma_f32 v[134:135], v[10:11], v[118:119], v[134:135]
	v_pk_fma_f32 v[132:133], v[4:5], v[120:121], v[132:133]
	v_pk_fma_f32 v[134:135], v[6:7], v[122:123], v[134:135]
	v_pk_fma_f32 v[132:133], v[0:1], v[124:125], v[132:133]
	v_pk_fma_f32 v[134:135], v[2:3], v[126:127], v[134:135]
	s_waitcnt lgkmcnt(8)
	ds_read_b128 v[112:115], v190 offset:1728
	ds_read_b128 v[116:119], v190 offset:1744
	ds_read_b128 v[120:123], v190 offset:1760
	ds_read_b128 v[124:127], v190 offset:1776
	v_pk_mul_f32 v[128:129], v[60:61], v[64:65]
	v_pk_mul_f32 v[130:131], v[62:63], v[66:67]
	v_pk_add_f32 v[132:133], v[132:133], v[134:135]
	v_pk_fma_f32 v[128:129], v[56:57], v[68:69], v[128:129]
	v_pk_fma_f32 v[130:131], v[58:59], v[70:71], v[130:131]
	v_add_f32_e32 v136, v132, v133
	v_pk_fma_f32 v[128:129], v[52:53], v[72:73], v[128:129]
	v_pk_fma_f32 v[130:131], v[54:55], v[74:75], v[130:131]
	v_add_f32_e32 v165, v165, v136
	v_pk_fma_f32 v[128:129], v[44:45], v[76:77], v[128:129]
	v_pk_fma_f32 v[130:131], v[46:47], v[78:79], v[130:131]
	s_waitcnt lgkmcnt(8)
	ds_read_b128 v[64:67], v190 offset:1792
	ds_read_b128 v[68:71], v190 offset:1808
	ds_read_b128 v[72:75], v190 offset:1824
	ds_read_b128 v[76:79], v190 offset:1840
	v_pk_fma_f32 v[128:129], v[48:49], v[80:81], v[128:129]
	v_pk_fma_f32 v[130:131], v[50:51], v[82:83], v[130:131]
	v_pk_fma_f32 v[128:129], v[40:41], v[84:85], v[128:129]
	v_pk_fma_f32 v[130:131], v[42:43], v[86:87], v[130:131]
	v_pk_fma_f32 v[128:129], v[36:37], v[88:89], v[128:129]
	v_pk_fma_f32 v[130:131], v[38:39], v[90:91], v[130:131]
	v_pk_fma_f32 v[128:129], v[32:33], v[92:93], v[128:129]
	v_pk_fma_f32 v[130:131], v[34:35], v[94:95], v[130:131]
	s_waitcnt lgkmcnt(8)
	ds_read_b128 v[80:83], v190 offset:1856
	ds_read_b128 v[84:87], v190 offset:1872
	ds_read_b128 v[88:91], v190 offset:1888
	ds_read_b128 v[92:95], v190 offset:1904
	v_pk_fma_f32 v[128:129], v[28:29], v[96:97], v[128:129]
	v_pk_fma_f32 v[130:131], v[30:31], v[98:99], v[130:131]
	v_pk_fma_f32 v[128:129], v[24:25], v[100:101], v[128:129]
	v_pk_fma_f32 v[130:131], v[26:27], v[102:103], v[130:131]
	v_pk_fma_f32 v[128:129], v[20:21], v[104:105], v[128:129]
	v_pk_fma_f32 v[130:131], v[22:23], v[106:107], v[130:131]
	v_pk_fma_f32 v[128:129], v[16:17], v[108:109], v[128:129]
	v_pk_fma_f32 v[130:131], v[18:19], v[110:111], v[130:131]
	s_waitcnt lgkmcnt(8)
	ds_read_b128 v[96:99], v190 offset:1920
	ds_read_b128 v[100:103], v190 offset:1936
	ds_read_b128 v[104:107], v190 offset:1952
	ds_read_b128 v[108:111], v190 offset:1968
	v_pk_fma_f32 v[128:129], v[12:13], v[112:113], v[128:129]
	v_pk_fma_f32 v[130:131], v[14:15], v[114:115], v[130:131]
	v_pk_fma_f32 v[128:129], v[8:9], v[116:117], v[128:129]
	v_pk_fma_f32 v[130:131], v[10:11], v[118:119], v[130:131]
	v_pk_fma_f32 v[128:129], v[4:5], v[120:121], v[128:129]
	v_pk_fma_f32 v[130:131], v[6:7], v[122:123], v[130:131]
	v_pk_fma_f32 v[128:129], v[0:1], v[124:125], v[128:129]
	v_pk_fma_f32 v[130:131], v[2:3], v[126:127], v[130:131]
	s_waitcnt lgkmcnt(8)
	ds_read_b128 v[112:115], v190 offset:1984
	ds_read_b128 v[116:119], v190 offset:2000
	ds_read_b128 v[120:123], v190 offset:2016
	ds_read_b128 v[124:127], v190 offset:2032
	v_pk_mul_f32 v[132:133], v[60:61], v[64:65]
	v_pk_mul_f32 v[134:135], v[62:63], v[66:67]
	v_pk_add_f32 v[128:129], v[128:129], v[130:131]
	v_pk_fma_f32 v[132:133], v[56:57], v[68:69], v[132:133]
	v_pk_fma_f32 v[134:135], v[58:59], v[70:71], v[134:135]
	v_add_f32_e32 v136, v128, v129
	v_pk_fma_f32 v[132:133], v[52:53], v[72:73], v[132:133]
	v_pk_fma_f32 v[134:135], v[54:55], v[74:75], v[134:135]
	v_add_f32_e32 v162, v162, v136
	v_pk_fma_f32 v[132:133], v[44:45], v[76:77], v[132:133]
	v_pk_fma_f32 v[134:135], v[46:47], v[78:79], v[134:135]
	s_waitcnt lgkmcnt(8)
	ds_read_b128 v[64:67], v190 offset:2048
	ds_read_b128 v[68:71], v190 offset:2064
	ds_read_b128 v[72:75], v190 offset:2080
	ds_read_b128 v[76:79], v190 offset:2096
	v_pk_fma_f32 v[132:133], v[48:49], v[80:81], v[132:133]
	v_pk_fma_f32 v[134:135], v[50:51], v[82:83], v[134:135]
	v_pk_fma_f32 v[132:133], v[40:41], v[84:85], v[132:133]
	v_pk_fma_f32 v[134:135], v[42:43], v[86:87], v[134:135]
	v_pk_fma_f32 v[132:133], v[36:37], v[88:89], v[132:133]
	v_pk_fma_f32 v[134:135], v[38:39], v[90:91], v[134:135]
	v_pk_fma_f32 v[132:133], v[32:33], v[92:93], v[132:133]
	v_pk_fma_f32 v[134:135], v[34:35], v[94:95], v[134:135]
	s_waitcnt lgkmcnt(8)
	ds_read_b128 v[80:83], v190 offset:2112
	ds_read_b128 v[84:87], v190 offset:2128
	ds_read_b128 v[88:91], v190 offset:2144
	ds_read_b128 v[92:95], v190 offset:2160
	v_pk_fma_f32 v[132:133], v[28:29], v[96:97], v[132:133]
	v_pk_fma_f32 v[134:135], v[30:31], v[98:99], v[134:135]
	v_pk_fma_f32 v[132:133], v[24:25], v[100:101], v[132:133]
	v_pk_fma_f32 v[134:135], v[26:27], v[102:103], v[134:135]
	v_pk_fma_f32 v[132:133], v[20:21], v[104:105], v[132:133]
	v_pk_fma_f32 v[134:135], v[22:23], v[106:107], v[134:135]
	v_pk_fma_f32 v[132:133], v[16:17], v[108:109], v[132:133]
	v_pk_fma_f32 v[134:135], v[18:19], v[110:111], v[134:135]
	s_waitcnt lgkmcnt(8)
	ds_read_b128 v[96:99], v190 offset:2176
	ds_read_b128 v[100:103], v190 offset:2192
	ds_read_b128 v[104:107], v190 offset:2208
	ds_read_b128 v[108:111], v190 offset:2224
	v_pk_fma_f32 v[132:133], v[12:13], v[112:113], v[132:133]
	v_pk_fma_f32 v[134:135], v[14:15], v[114:115], v[134:135]
	v_pk_fma_f32 v[132:133], v[8:9], v[116:117], v[132:133]
	v_pk_fma_f32 v[134:135], v[10:11], v[118:119], v[134:135]
	v_pk_fma_f32 v[132:133], v[4:5], v[120:121], v[132:133]
	v_pk_fma_f32 v[134:135], v[6:7], v[122:123], v[134:135]
	v_pk_fma_f32 v[132:133], v[0:1], v[124:125], v[132:133]
	v_pk_fma_f32 v[134:135], v[2:3], v[126:127], v[134:135]
	s_waitcnt lgkmcnt(8)
	ds_read_b128 v[112:115], v190 offset:2240
	ds_read_b128 v[116:119], v190 offset:2256
	ds_read_b128 v[120:123], v190 offset:2272
	ds_read_b128 v[124:127], v190 offset:2288
	v_pk_mul_f32 v[128:129], v[60:61], v[64:65]
	v_pk_mul_f32 v[130:131], v[62:63], v[66:67]
	v_pk_add_f32 v[132:133], v[132:133], v[134:135]
	v_pk_fma_f32 v[128:129], v[56:57], v[68:69], v[128:129]
	v_pk_fma_f32 v[130:131], v[58:59], v[70:71], v[130:131]
	v_add_f32_e32 v136, v132, v133
	v_pk_fma_f32 v[128:129], v[52:53], v[72:73], v[128:129]
	v_pk_fma_f32 v[130:131], v[54:55], v[74:75], v[130:131]
	v_add_f32_e32 v163, v163, v136
	v_pk_fma_f32 v[128:129], v[44:45], v[76:77], v[128:129]
	v_pk_fma_f32 v[130:131], v[46:47], v[78:79], v[130:131]
	s_waitcnt lgkmcnt(8)
	ds_read_b128 v[64:67], v190 offset:2304
	ds_read_b128 v[68:71], v190 offset:2320
	ds_read_b128 v[72:75], v190 offset:2336
	ds_read_b128 v[76:79], v190 offset:2352
	v_pk_fma_f32 v[128:129], v[48:49], v[80:81], v[128:129]
	v_pk_fma_f32 v[130:131], v[50:51], v[82:83], v[130:131]
	v_pk_fma_f32 v[128:129], v[40:41], v[84:85], v[128:129]
	v_pk_fma_f32 v[130:131], v[42:43], v[86:87], v[130:131]
	v_pk_fma_f32 v[128:129], v[36:37], v[88:89], v[128:129]
	v_pk_fma_f32 v[130:131], v[38:39], v[90:91], v[130:131]
	v_pk_fma_f32 v[128:129], v[32:33], v[92:93], v[128:129]
	v_pk_fma_f32 v[130:131], v[34:35], v[94:95], v[130:131]
	s_waitcnt lgkmcnt(8)
	ds_read_b128 v[80:83], v190 offset:2368
	ds_read_b128 v[84:87], v190 offset:2384
	ds_read_b128 v[88:91], v190 offset:2400
	ds_read_b128 v[92:95], v190 offset:2416
	v_pk_fma_f32 v[128:129], v[28:29], v[96:97], v[128:129]
	v_pk_fma_f32 v[130:131], v[30:31], v[98:99], v[130:131]
	v_pk_fma_f32 v[128:129], v[24:25], v[100:101], v[128:129]
	v_pk_fma_f32 v[130:131], v[26:27], v[102:103], v[130:131]
	v_pk_fma_f32 v[128:129], v[20:21], v[104:105], v[128:129]
	v_pk_fma_f32 v[130:131], v[22:23], v[106:107], v[130:131]
	v_pk_fma_f32 v[128:129], v[16:17], v[108:109], v[128:129]
	v_pk_fma_f32 v[130:131], v[18:19], v[110:111], v[130:131]
	s_waitcnt lgkmcnt(8)
	ds_read_b128 v[96:99], v190 offset:2432
	ds_read_b128 v[100:103], v190 offset:2448
	ds_read_b128 v[104:107], v190 offset:2464
	ds_read_b128 v[108:111], v190 offset:2480
	v_pk_fma_f32 v[128:129], v[12:13], v[112:113], v[128:129]
	v_pk_fma_f32 v[130:131], v[14:15], v[114:115], v[130:131]
	v_pk_fma_f32 v[128:129], v[8:9], v[116:117], v[128:129]
	v_pk_fma_f32 v[130:131], v[10:11], v[118:119], v[130:131]
	v_pk_fma_f32 v[128:129], v[4:5], v[120:121], v[128:129]
	v_pk_fma_f32 v[130:131], v[6:7], v[122:123], v[130:131]
	v_pk_fma_f32 v[128:129], v[0:1], v[124:125], v[128:129]
	v_pk_fma_f32 v[130:131], v[2:3], v[126:127], v[130:131]
	s_waitcnt lgkmcnt(8)
	ds_read_b128 v[112:115], v190 offset:2496
	ds_read_b128 v[116:119], v190 offset:2512
	ds_read_b128 v[120:123], v190 offset:2528
	ds_read_b128 v[124:127], v190 offset:2544
	v_pk_mul_f32 v[132:133], v[60:61], v[64:65]
	v_pk_mul_f32 v[134:135], v[62:63], v[66:67]
	v_pk_add_f32 v[128:129], v[128:129], v[130:131]
	v_pk_fma_f32 v[132:133], v[56:57], v[68:69], v[132:133]
	v_pk_fma_f32 v[134:135], v[58:59], v[70:71], v[134:135]
	v_add_f32_e32 v136, v128, v129
	v_pk_fma_f32 v[132:133], v[52:53], v[72:73], v[132:133]
	v_pk_fma_f32 v[134:135], v[54:55], v[74:75], v[134:135]
	v_add_f32_e32 v160, v160, v136
	v_pk_fma_f32 v[132:133], v[44:45], v[76:77], v[132:133]
	v_pk_fma_f32 v[134:135], v[46:47], v[78:79], v[134:135]
	s_waitcnt lgkmcnt(8)
	ds_read_b128 v[64:67], v190 offset:2560
	ds_read_b128 v[68:71], v190 offset:2576
	ds_read_b128 v[72:75], v190 offset:2592
	ds_read_b128 v[76:79], v190 offset:2608
	v_pk_fma_f32 v[132:133], v[48:49], v[80:81], v[132:133]
	v_pk_fma_f32 v[134:135], v[50:51], v[82:83], v[134:135]
	v_pk_fma_f32 v[132:133], v[40:41], v[84:85], v[132:133]
	v_pk_fma_f32 v[134:135], v[42:43], v[86:87], v[134:135]
	v_pk_fma_f32 v[132:133], v[36:37], v[88:89], v[132:133]
	v_pk_fma_f32 v[134:135], v[38:39], v[90:91], v[134:135]
	v_pk_fma_f32 v[132:133], v[32:33], v[92:93], v[132:133]
	v_pk_fma_f32 v[134:135], v[34:35], v[94:95], v[134:135]
	s_waitcnt lgkmcnt(8)
	ds_read_b128 v[80:83], v190 offset:2624
	ds_read_b128 v[84:87], v190 offset:2640
	ds_read_b128 v[88:91], v190 offset:2656
	ds_read_b128 v[92:95], v190 offset:2672
	v_pk_fma_f32 v[132:133], v[28:29], v[96:97], v[132:133]
	v_pk_fma_f32 v[134:135], v[30:31], v[98:99], v[134:135]
	v_pk_fma_f32 v[132:133], v[24:25], v[100:101], v[132:133]
	v_pk_fma_f32 v[134:135], v[26:27], v[102:103], v[134:135]
	v_pk_fma_f32 v[132:133], v[20:21], v[104:105], v[132:133]
	v_pk_fma_f32 v[134:135], v[22:23], v[106:107], v[134:135]
	v_pk_fma_f32 v[132:133], v[16:17], v[108:109], v[132:133]
	v_pk_fma_f32 v[134:135], v[18:19], v[110:111], v[134:135]
	s_waitcnt lgkmcnt(8)
	ds_read_b128 v[96:99], v190 offset:2688
	ds_read_b128 v[100:103], v190 offset:2704
	ds_read_b128 v[104:107], v190 offset:2720
	ds_read_b128 v[108:111], v190 offset:2736
	v_pk_fma_f32 v[132:133], v[12:13], v[112:113], v[132:133]
	v_pk_fma_f32 v[134:135], v[14:15], v[114:115], v[134:135]
	v_pk_fma_f32 v[132:133], v[8:9], v[116:117], v[132:133]
	v_pk_fma_f32 v[134:135], v[10:11], v[118:119], v[134:135]
	v_pk_fma_f32 v[132:133], v[4:5], v[120:121], v[132:133]
	v_pk_fma_f32 v[134:135], v[6:7], v[122:123], v[134:135]
	v_pk_fma_f32 v[132:133], v[0:1], v[124:125], v[132:133]
	v_pk_fma_f32 v[134:135], v[2:3], v[126:127], v[134:135]
	s_waitcnt lgkmcnt(8)
	ds_read_b128 v[112:115], v190 offset:2752
	ds_read_b128 v[116:119], v190 offset:2768
	ds_read_b128 v[120:123], v190 offset:2784
	ds_read_b128 v[124:127], v190 offset:2800
	v_pk_mul_f32 v[128:129], v[60:61], v[64:65]
	v_pk_mul_f32 v[130:131], v[62:63], v[66:67]
	v_pk_add_f32 v[132:133], v[132:133], v[134:135]
	v_pk_fma_f32 v[128:129], v[56:57], v[68:69], v[128:129]
	v_pk_fma_f32 v[130:131], v[58:59], v[70:71], v[130:131]
	v_add_f32_e32 v136, v132, v133
	v_pk_fma_f32 v[128:129], v[52:53], v[72:73], v[128:129]
	v_pk_fma_f32 v[130:131], v[54:55], v[74:75], v[130:131]
	v_add_f32_e32 v161, v161, v136
	v_pk_fma_f32 v[128:129], v[44:45], v[76:77], v[128:129]
	v_pk_fma_f32 v[130:131], v[46:47], v[78:79], v[130:131]
	s_waitcnt lgkmcnt(8)
	ds_read_b128 v[64:67], v190 offset:2816
	ds_read_b128 v[68:71], v190 offset:2832
	ds_read_b128 v[72:75], v190 offset:2848
	ds_read_b128 v[76:79], v190 offset:2864
	v_pk_fma_f32 v[128:129], v[48:49], v[80:81], v[128:129]
	v_pk_fma_f32 v[130:131], v[50:51], v[82:83], v[130:131]
	v_pk_fma_f32 v[128:129], v[40:41], v[84:85], v[128:129]
	v_pk_fma_f32 v[130:131], v[42:43], v[86:87], v[130:131]
	v_pk_fma_f32 v[128:129], v[36:37], v[88:89], v[128:129]
	v_pk_fma_f32 v[130:131], v[38:39], v[90:91], v[130:131]
	v_pk_fma_f32 v[128:129], v[32:33], v[92:93], v[128:129]
	v_pk_fma_f32 v[130:131], v[34:35], v[94:95], v[130:131]
	s_waitcnt lgkmcnt(8)
	ds_read_b128 v[80:83], v190 offset:2880
	ds_read_b128 v[84:87], v190 offset:2896
	ds_read_b128 v[88:91], v190 offset:2912
	ds_read_b128 v[92:95], v190 offset:2928
	v_pk_fma_f32 v[128:129], v[28:29], v[96:97], v[128:129]
	v_pk_fma_f32 v[130:131], v[30:31], v[98:99], v[130:131]
	v_pk_fma_f32 v[128:129], v[24:25], v[100:101], v[128:129]
	v_pk_fma_f32 v[130:131], v[26:27], v[102:103], v[130:131]
	v_pk_fma_f32 v[128:129], v[20:21], v[104:105], v[128:129]
	v_pk_fma_f32 v[130:131], v[22:23], v[106:107], v[130:131]
	v_pk_fma_f32 v[128:129], v[16:17], v[108:109], v[128:129]
	v_pk_fma_f32 v[130:131], v[18:19], v[110:111], v[130:131]
	s_waitcnt lgkmcnt(8)
	ds_read_b128 v[96:99], v190 offset:2944
	ds_read_b128 v[100:103], v190 offset:2960
	ds_read_b128 v[104:107], v190 offset:2976
	ds_read_b128 v[108:111], v190 offset:2992
	v_pk_fma_f32 v[128:129], v[12:13], v[112:113], v[128:129]
	v_pk_fma_f32 v[130:131], v[14:15], v[114:115], v[130:131]
	v_pk_fma_f32 v[128:129], v[8:9], v[116:117], v[128:129]
	v_pk_fma_f32 v[130:131], v[10:11], v[118:119], v[130:131]
	v_pk_fma_f32 v[128:129], v[4:5], v[120:121], v[128:129]
	v_pk_fma_f32 v[130:131], v[6:7], v[122:123], v[130:131]
	v_pk_fma_f32 v[128:129], v[0:1], v[124:125], v[128:129]
	v_pk_fma_f32 v[130:131], v[2:3], v[126:127], v[130:131]
	s_waitcnt lgkmcnt(8)
	ds_read_b128 v[112:115], v190 offset:3008
	ds_read_b128 v[116:119], v190 offset:3024
	ds_read_b128 v[120:123], v190 offset:3040
	ds_read_b128 v[124:127], v190 offset:3056
	v_pk_mul_f32 v[132:133], v[60:61], v[64:65]
	v_pk_mul_f32 v[134:135], v[62:63], v[66:67]
	v_pk_add_f32 v[128:129], v[128:129], v[130:131]
	v_pk_fma_f32 v[132:133], v[56:57], v[68:69], v[132:133]
	v_pk_fma_f32 v[134:135], v[58:59], v[70:71], v[134:135]
	v_add_f32_e32 v136, v128, v129
	v_pk_fma_f32 v[132:133], v[52:53], v[72:73], v[132:133]
	v_pk_fma_f32 v[134:135], v[54:55], v[74:75], v[134:135]
	v_add_f32_e32 v158, v158, v136
	v_pk_fma_f32 v[132:133], v[44:45], v[76:77], v[132:133]
	v_pk_fma_f32 v[134:135], v[46:47], v[78:79], v[134:135]
	s_waitcnt lgkmcnt(8)
	ds_read_b128 v[64:67], v190 offset:3072
	ds_read_b128 v[68:71], v190 offset:3088
	ds_read_b128 v[72:75], v190 offset:3104
	ds_read_b128 v[76:79], v190 offset:3120
	v_pk_fma_f32 v[132:133], v[48:49], v[80:81], v[132:133]
	v_pk_fma_f32 v[134:135], v[50:51], v[82:83], v[134:135]
	v_pk_fma_f32 v[132:133], v[40:41], v[84:85], v[132:133]
	v_pk_fma_f32 v[134:135], v[42:43], v[86:87], v[134:135]
	v_pk_fma_f32 v[132:133], v[36:37], v[88:89], v[132:133]
	v_pk_fma_f32 v[134:135], v[38:39], v[90:91], v[134:135]
	v_pk_fma_f32 v[132:133], v[32:33], v[92:93], v[132:133]
	v_pk_fma_f32 v[134:135], v[34:35], v[94:95], v[134:135]
	s_waitcnt lgkmcnt(8)
	ds_read_b128 v[80:83], v190 offset:3136
	ds_read_b128 v[84:87], v190 offset:3152
	ds_read_b128 v[88:91], v190 offset:3168
	ds_read_b128 v[92:95], v190 offset:3184
	v_pk_fma_f32 v[132:133], v[28:29], v[96:97], v[132:133]
	v_pk_fma_f32 v[134:135], v[30:31], v[98:99], v[134:135]
	v_pk_fma_f32 v[132:133], v[24:25], v[100:101], v[132:133]
	v_pk_fma_f32 v[134:135], v[26:27], v[102:103], v[134:135]
	v_pk_fma_f32 v[132:133], v[20:21], v[104:105], v[132:133]
	v_pk_fma_f32 v[134:135], v[22:23], v[106:107], v[134:135]
	v_pk_fma_f32 v[132:133], v[16:17], v[108:109], v[132:133]
	v_pk_fma_f32 v[134:135], v[18:19], v[110:111], v[134:135]
	s_waitcnt lgkmcnt(8)
	ds_read_b128 v[96:99], v190 offset:3200
	ds_read_b128 v[100:103], v190 offset:3216
	ds_read_b128 v[104:107], v190 offset:3232
	ds_read_b128 v[108:111], v190 offset:3248
	v_pk_fma_f32 v[132:133], v[12:13], v[112:113], v[132:133]
	v_pk_fma_f32 v[134:135], v[14:15], v[114:115], v[134:135]
	v_pk_fma_f32 v[132:133], v[8:9], v[116:117], v[132:133]
	v_pk_fma_f32 v[134:135], v[10:11], v[118:119], v[134:135]
	v_pk_fma_f32 v[132:133], v[4:5], v[120:121], v[132:133]
	v_pk_fma_f32 v[134:135], v[6:7], v[122:123], v[134:135]
	v_pk_fma_f32 v[132:133], v[0:1], v[124:125], v[132:133]
	v_pk_fma_f32 v[134:135], v[2:3], v[126:127], v[134:135]
	s_waitcnt lgkmcnt(8)
	ds_read_b128 v[112:115], v190 offset:3264
	ds_read_b128 v[116:119], v190 offset:3280
	ds_read_b128 v[120:123], v190 offset:3296
	ds_read_b128 v[124:127], v190 offset:3312
	v_pk_mul_f32 v[128:129], v[60:61], v[64:65]
	v_pk_mul_f32 v[130:131], v[62:63], v[66:67]
	v_pk_add_f32 v[132:133], v[132:133], v[134:135]
	v_pk_fma_f32 v[128:129], v[56:57], v[68:69], v[128:129]
	v_pk_fma_f32 v[130:131], v[58:59], v[70:71], v[130:131]
	v_add_f32_e32 v136, v132, v133
	v_pk_fma_f32 v[128:129], v[52:53], v[72:73], v[128:129]
	v_pk_fma_f32 v[130:131], v[54:55], v[74:75], v[130:131]
	v_add_f32_e32 v159, v159, v136
	v_pk_fma_f32 v[128:129], v[44:45], v[76:77], v[128:129]
	v_pk_fma_f32 v[130:131], v[46:47], v[78:79], v[130:131]
	s_waitcnt lgkmcnt(8)
	ds_read_b128 v[64:67], v190 offset:3328
	ds_read_b128 v[68:71], v190 offset:3344
	ds_read_b128 v[72:75], v190 offset:3360
	ds_read_b128 v[76:79], v190 offset:3376
	v_pk_fma_f32 v[128:129], v[48:49], v[80:81], v[128:129]
	v_pk_fma_f32 v[130:131], v[50:51], v[82:83], v[130:131]
	v_pk_fma_f32 v[128:129], v[40:41], v[84:85], v[128:129]
	v_pk_fma_f32 v[130:131], v[42:43], v[86:87], v[130:131]
	v_pk_fma_f32 v[128:129], v[36:37], v[88:89], v[128:129]
	v_pk_fma_f32 v[130:131], v[38:39], v[90:91], v[130:131]
	v_pk_fma_f32 v[128:129], v[32:33], v[92:93], v[128:129]
	v_pk_fma_f32 v[130:131], v[34:35], v[94:95], v[130:131]
	s_waitcnt lgkmcnt(8)
	ds_read_b128 v[80:83], v190 offset:3392
	ds_read_b128 v[84:87], v190 offset:3408
	ds_read_b128 v[88:91], v190 offset:3424
	ds_read_b128 v[92:95], v190 offset:3440
	v_pk_fma_f32 v[128:129], v[28:29], v[96:97], v[128:129]
	v_pk_fma_f32 v[130:131], v[30:31], v[98:99], v[130:131]
	v_pk_fma_f32 v[128:129], v[24:25], v[100:101], v[128:129]
	v_pk_fma_f32 v[130:131], v[26:27], v[102:103], v[130:131]
	v_pk_fma_f32 v[128:129], v[20:21], v[104:105], v[128:129]
	v_pk_fma_f32 v[130:131], v[22:23], v[106:107], v[130:131]
	v_pk_fma_f32 v[128:129], v[16:17], v[108:109], v[128:129]
	v_pk_fma_f32 v[130:131], v[18:19], v[110:111], v[130:131]
	s_waitcnt lgkmcnt(8)
	ds_read_b128 v[96:99], v190 offset:3456
	ds_read_b128 v[100:103], v190 offset:3472
	ds_read_b128 v[104:107], v190 offset:3488
	ds_read_b128 v[108:111], v190 offset:3504
	v_pk_fma_f32 v[128:129], v[12:13], v[112:113], v[128:129]
	v_pk_fma_f32 v[130:131], v[14:15], v[114:115], v[130:131]
	v_pk_fma_f32 v[128:129], v[8:9], v[116:117], v[128:129]
	v_pk_fma_f32 v[130:131], v[10:11], v[118:119], v[130:131]
	v_pk_fma_f32 v[128:129], v[4:5], v[120:121], v[128:129]
	v_pk_fma_f32 v[130:131], v[6:7], v[122:123], v[130:131]
	v_pk_fma_f32 v[128:129], v[0:1], v[124:125], v[128:129]
	v_pk_fma_f32 v[130:131], v[2:3], v[126:127], v[130:131]
	s_waitcnt lgkmcnt(8)
	ds_read_b128 v[112:115], v190 offset:3520
	ds_read_b128 v[116:119], v190 offset:3536
	ds_read_b128 v[120:123], v190 offset:3552
	ds_read_b128 v[124:127], v190 offset:3568
	v_pk_mul_f32 v[132:133], v[60:61], v[64:65]
	v_pk_mul_f32 v[134:135], v[62:63], v[66:67]
	v_pk_add_f32 v[128:129], v[128:129], v[130:131]
	v_pk_fma_f32 v[132:133], v[56:57], v[68:69], v[132:133]
	v_pk_fma_f32 v[134:135], v[58:59], v[70:71], v[134:135]
	v_add_f32_e32 v136, v128, v129
	v_pk_fma_f32 v[132:133], v[52:53], v[72:73], v[132:133]
	v_pk_fma_f32 v[134:135], v[54:55], v[74:75], v[134:135]
	v_add_f32_e32 v156, v156, v136
	v_pk_fma_f32 v[132:133], v[44:45], v[76:77], v[132:133]
	v_pk_fma_f32 v[134:135], v[46:47], v[78:79], v[134:135]
	s_waitcnt lgkmcnt(8)
	ds_read_b128 v[64:67], v190 offset:3584
	ds_read_b128 v[68:71], v190 offset:3600
	ds_read_b128 v[72:75], v190 offset:3616
	ds_read_b128 v[76:79], v190 offset:3632
	v_pk_fma_f32 v[132:133], v[48:49], v[80:81], v[132:133]
	v_pk_fma_f32 v[134:135], v[50:51], v[82:83], v[134:135]
	v_pk_fma_f32 v[132:133], v[40:41], v[84:85], v[132:133]
	v_pk_fma_f32 v[134:135], v[42:43], v[86:87], v[134:135]
	v_pk_fma_f32 v[132:133], v[36:37], v[88:89], v[132:133]
	v_pk_fma_f32 v[134:135], v[38:39], v[90:91], v[134:135]
	v_pk_fma_f32 v[132:133], v[32:33], v[92:93], v[132:133]
	v_pk_fma_f32 v[134:135], v[34:35], v[94:95], v[134:135]
	s_waitcnt lgkmcnt(8)
	ds_read_b128 v[80:83], v190 offset:3648
	ds_read_b128 v[84:87], v190 offset:3664
	ds_read_b128 v[88:91], v190 offset:3680
	ds_read_b128 v[92:95], v190 offset:3696
	v_pk_fma_f32 v[132:133], v[28:29], v[96:97], v[132:133]
	v_pk_fma_f32 v[134:135], v[30:31], v[98:99], v[134:135]
	v_pk_fma_f32 v[132:133], v[24:25], v[100:101], v[132:133]
	v_pk_fma_f32 v[134:135], v[26:27], v[102:103], v[134:135]
	v_pk_fma_f32 v[132:133], v[20:21], v[104:105], v[132:133]
	v_pk_fma_f32 v[134:135], v[22:23], v[106:107], v[134:135]
	v_pk_fma_f32 v[132:133], v[16:17], v[108:109], v[132:133]
	v_pk_fma_f32 v[134:135], v[18:19], v[110:111], v[134:135]
	s_waitcnt lgkmcnt(8)
	ds_read_b128 v[96:99], v190 offset:3712
	ds_read_b128 v[100:103], v190 offset:3728
	ds_read_b128 v[104:107], v190 offset:3744
	ds_read_b128 v[108:111], v190 offset:3760
	v_pk_fma_f32 v[132:133], v[12:13], v[112:113], v[132:133]
	v_pk_fma_f32 v[134:135], v[14:15], v[114:115], v[134:135]
	v_pk_fma_f32 v[132:133], v[8:9], v[116:117], v[132:133]
	v_pk_fma_f32 v[134:135], v[10:11], v[118:119], v[134:135]
	v_pk_fma_f32 v[132:133], v[4:5], v[120:121], v[132:133]
	v_pk_fma_f32 v[134:135], v[6:7], v[122:123], v[134:135]
	v_pk_fma_f32 v[132:133], v[0:1], v[124:125], v[132:133]
	v_pk_fma_f32 v[134:135], v[2:3], v[126:127], v[134:135]
	s_waitcnt lgkmcnt(8)
	ds_read_b128 v[112:115], v190 offset:3776
	ds_read_b128 v[116:119], v190 offset:3792
	ds_read_b128 v[120:123], v190 offset:3808
	ds_read_b128 v[124:127], v190 offset:3824
	v_pk_mul_f32 v[128:129], v[60:61], v[64:65]
	v_pk_mul_f32 v[130:131], v[62:63], v[66:67]
	v_pk_add_f32 v[132:133], v[132:133], v[134:135]
	v_pk_fma_f32 v[128:129], v[56:57], v[68:69], v[128:129]
	v_pk_fma_f32 v[130:131], v[58:59], v[70:71], v[130:131]
	v_add_f32_e32 v136, v132, v133
	v_pk_fma_f32 v[128:129], v[52:53], v[72:73], v[128:129]
	v_pk_fma_f32 v[130:131], v[54:55], v[74:75], v[130:131]
	v_add_f32_e32 v157, v157, v136
	v_pk_fma_f32 v[128:129], v[44:45], v[76:77], v[128:129]
	v_pk_fma_f32 v[130:131], v[46:47], v[78:79], v[130:131]
	s_waitcnt lgkmcnt(8)
	ds_read_b128 v[64:67], v190 offset:3840
	ds_read_b128 v[68:71], v190 offset:3856
	ds_read_b128 v[72:75], v190 offset:3872
	ds_read_b128 v[76:79], v190 offset:3888
	v_pk_fma_f32 v[128:129], v[48:49], v[80:81], v[128:129]
	v_pk_fma_f32 v[130:131], v[50:51], v[82:83], v[130:131]
	v_pk_fma_f32 v[128:129], v[40:41], v[84:85], v[128:129]
	v_pk_fma_f32 v[130:131], v[42:43], v[86:87], v[130:131]
	v_pk_fma_f32 v[128:129], v[36:37], v[88:89], v[128:129]
	v_pk_fma_f32 v[130:131], v[38:39], v[90:91], v[130:131]
	v_pk_fma_f32 v[128:129], v[32:33], v[92:93], v[128:129]
	v_pk_fma_f32 v[130:131], v[34:35], v[94:95], v[130:131]
	s_waitcnt lgkmcnt(8)
	ds_read_b128 v[80:83], v190 offset:3904
	ds_read_b128 v[84:87], v190 offset:3920
	ds_read_b128 v[88:91], v190 offset:3936
	ds_read_b128 v[92:95], v190 offset:3952
	v_pk_fma_f32 v[128:129], v[28:29], v[96:97], v[128:129]
	v_pk_fma_f32 v[130:131], v[30:31], v[98:99], v[130:131]
	v_pk_fma_f32 v[128:129], v[24:25], v[100:101], v[128:129]
	v_pk_fma_f32 v[130:131], v[26:27], v[102:103], v[130:131]
	v_pk_fma_f32 v[128:129], v[20:21], v[104:105], v[128:129]
	v_pk_fma_f32 v[130:131], v[22:23], v[106:107], v[130:131]
	v_pk_fma_f32 v[128:129], v[16:17], v[108:109], v[128:129]
	v_pk_fma_f32 v[130:131], v[18:19], v[110:111], v[130:131]
	s_waitcnt lgkmcnt(8)
	ds_read_b128 v[96:99], v190 offset:3968
	ds_read_b128 v[100:103], v190 offset:3984
	ds_read_b128 v[104:107], v190 offset:4000
	ds_read_b128 v[108:111], v190 offset:4016
	v_pk_fma_f32 v[128:129], v[12:13], v[112:113], v[128:129]
	v_pk_fma_f32 v[130:131], v[14:15], v[114:115], v[130:131]
	v_pk_fma_f32 v[128:129], v[8:9], v[116:117], v[128:129]
	v_pk_fma_f32 v[130:131], v[10:11], v[118:119], v[130:131]
	v_pk_fma_f32 v[128:129], v[4:5], v[120:121], v[128:129]
	v_pk_fma_f32 v[130:131], v[6:7], v[122:123], v[130:131]
	v_pk_fma_f32 v[128:129], v[0:1], v[124:125], v[128:129]
	v_pk_fma_f32 v[130:131], v[2:3], v[126:127], v[130:131]
	s_waitcnt lgkmcnt(8)
	ds_read_b128 v[112:115], v190 offset:4032
	ds_read_b128 v[116:119], v190 offset:4048
	ds_read_b128 v[120:123], v190 offset:4064
	ds_read_b128 v[124:127], v190 offset:4080
	v_pk_mul_f32 v[132:133], v[60:61], v[64:65]
	v_pk_mul_f32 v[134:135], v[62:63], v[66:67]
	v_pk_add_f32 v[128:129], v[128:129], v[130:131]
	v_pk_fma_f32 v[132:133], v[56:57], v[68:69], v[132:133]
	v_pk_fma_f32 v[134:135], v[58:59], v[70:71], v[134:135]
	v_add_f32_e32 v136, v128, v129
	v_pk_fma_f32 v[132:133], v[52:53], v[72:73], v[132:133]
	v_pk_fma_f32 v[134:135], v[54:55], v[74:75], v[134:135]
	v_add_f32_e32 v154, v154, v136
	v_pk_fma_f32 v[132:133], v[44:45], v[76:77], v[132:133]
	v_pk_fma_f32 v[134:135], v[46:47], v[78:79], v[134:135]
	s_waitcnt lgkmcnt(8)
	v_pk_fma_f32 v[132:133], v[48:49], v[80:81], v[132:133]
	v_pk_fma_f32 v[134:135], v[50:51], v[82:83], v[134:135]
	v_pk_fma_f32 v[132:133], v[40:41], v[84:85], v[132:133]
	v_pk_fma_f32 v[134:135], v[42:43], v[86:87], v[134:135]
	v_pk_fma_f32 v[132:133], v[36:37], v[88:89], v[132:133]
	v_pk_fma_f32 v[134:135], v[38:39], v[90:91], v[134:135]
	v_pk_fma_f32 v[132:133], v[32:33], v[92:93], v[132:133]
	v_pk_fma_f32 v[134:135], v[34:35], v[94:95], v[134:135]
	s_waitcnt lgkmcnt(4)
	v_pk_fma_f32 v[132:133], v[28:29], v[96:97], v[132:133]
	v_pk_fma_f32 v[134:135], v[30:31], v[98:99], v[134:135]
	v_pk_fma_f32 v[132:133], v[24:25], v[100:101], v[132:133]
	v_pk_fma_f32 v[134:135], v[26:27], v[102:103], v[134:135]
	v_pk_fma_f32 v[132:133], v[20:21], v[104:105], v[132:133]
	v_pk_fma_f32 v[134:135], v[22:23], v[106:107], v[134:135]
	v_pk_fma_f32 v[132:133], v[16:17], v[108:109], v[132:133]
	v_pk_fma_f32 v[134:135], v[18:19], v[110:111], v[134:135]
	s_waitcnt lgkmcnt(0)
	v_pk_fma_f32 v[132:133], v[12:13], v[112:113], v[132:133]
	v_pk_fma_f32 v[134:135], v[14:15], v[114:115], v[134:135]
	v_pk_fma_f32 v[132:133], v[8:9], v[116:117], v[132:133]
	v_pk_fma_f32 v[134:135], v[10:11], v[118:119], v[134:135]
	v_pk_fma_f32 v[132:133], v[4:5], v[120:121], v[132:133]
	v_pk_fma_f32 v[134:135], v[6:7], v[122:123], v[134:135]
	v_pk_fma_f32 v[132:133], v[0:1], v[124:125], v[132:133]
	v_pk_fma_f32 v[134:135], v[2:3], v[126:127], v[134:135]
	s_nop 0
	v_pk_add_f32 v[132:133], v[132:133], v[134:135]
	s_nop 0
	v_add_f32_e32 v136, v132, v133
	s_nop 0
	v_add_f32_e32 v155, v155, v136
	s_nop 0
	s_branch .LBB0_663
